# attention QK: 4 K-fragment ds_reads per 16-key block issued up front with counted lgkmcnt (was read-wait-MFMA in series)
# baseline (speedup 1.0000x reference)
; #define LAS __attribute__((address_space(3)))
; __device__ __forceinline__ void attn_phase(const Params& p, LAS unsigned char* lds, int l, int mode) {
;     ...
;             f32x4 sacc[10];
; #pragma unroll
;             for (int i = 0; i < 10; ++i) {
;                 sacc[i] = (f32x4){0.f, 0.f, 0.f, 0.f};
;                 const int kb = kb0 + i, koff = (kb < 8) ? koffP + kb * (16 * 272) : koffC + (kb - 8) * (16 * 272);
; #pragma unroll
;                 for (int s = 0; s < 4; ++s) {
;                     const bf16x8 kf = *(const LAS bf16x8*)(Kl + koff + li * 272 + (32 * s + 8 * g) * 2);
;                     sacc[i] = __builtin_amdgcn_mfma_f32_16x16x32_bf16(kf, qc[s], sacc[i], 0, 0, 0);
;                 }
;             }
.LBB0_231:
	s_lshl_b32 s43, s42, 7
	s_xor_b32 s42, s57, 1
	s_mul_i32 s57, s42, 0x8800
	s_add_i32 s56, s56, 0xffff7800
	v_mov_b32_e32 v105, s56
	v_mov_b32_e32 v106, s57
	v_cndmask_b32_e64 v52, v105, v106, s[36:37]
	v_add_u32_e32 v60, v108, v52
	ds_read_b128 v[52:55], v60
	ds_read_b128 v[56:59], v60 offset:64
	ds_read_b128 v[208:211], v60 offset:128
	ds_read_b128 v[212:215], v60 offset:192
	v_readlane_b32 s56, v254, 45
	v_readlane_b32 s57, v254, 46
	v_cndmask_b32_e64 v107, v105, v106, s[48:49]
	v_add_u32_e32 v104, s43, v141
	s_waitcnt lgkmcnt(3)
	v_mfma_f32_16x16x32_bf16 v[52:55], v[52:55], v[48:51], 0
	s_sub_i32 s43, 0x7f, s43
	v_cmp_lt_i32_e32 vcc, s43, v159
	s_mul_i32 s42, s42, 0x9000
	s_waitcnt lgkmcnt(2)
	v_mfma_f32_16x16x32_bf16 v[52:55], v[56:59], v[88:91], v[52:55]
	s_waitcnt lgkmcnt(1)
	v_mfma_f32_16x16x32_bf16 v[52:55], v[208:211], v[92:95], v[52:55]
	s_waitcnt lgkmcnt(0)
	v_mfma_f32_16x16x32_bf16 v[84:87], v[212:215], v[96:99], v[52:55]
	s_nop 4
	v_cndmask_b32_e64 v52, v105, v106, s[56:57]
	v_add_u32_e32 v60, v110, v52
	ds_read_b128 v[52:55], v60
	ds_read_b128 v[56:59], v60 offset:64
	ds_read_b128 v[208:211], v60 offset:128
	ds_read_b128 v[212:215], v60 offset:192
	v_readlane_b32 s56, v254, 47
	s_waitcnt lgkmcnt(3)
	v_mfma_f32_16x16x32_bf16 v[52:55], v[52:55], v[48:51], 0
	v_readlane_b32 s57, v254, 48
	s_waitcnt lgkmcnt(2)
	v_mfma_f32_16x16x32_bf16 v[52:55], v[56:59], v[88:91], v[52:55]
	s_waitcnt lgkmcnt(1)
	v_mfma_f32_16x16x32_bf16 v[52:55], v[208:211], v[92:95], v[52:55]
	s_waitcnt lgkmcnt(0)
	v_mfma_f32_16x16x32_bf16 v[80:83], v[212:215], v[96:99], v[52:55]
	s_nop 4
	v_cndmask_b32_e64 v52, v105, v106, s[40:41]
	v_add_u32_e32 v60, v109, v52
	ds_read_b128 v[52:55], v60
	ds_read_b128 v[56:59], v60 offset:64
	ds_read_b128 v[208:211], v60 offset:128
	ds_read_b128 v[212:215], v60 offset:192
	s_waitcnt lgkmcnt(3)
	v_mfma_f32_16x16x32_bf16 v[52:55], v[52:55], v[48:51], 0
	s_waitcnt lgkmcnt(2)
	v_mfma_f32_16x16x32_bf16 v[52:55], v[56:59], v[88:91], v[52:55]
	s_waitcnt lgkmcnt(1)
	v_mfma_f32_16x16x32_bf16 v[52:55], v[208:211], v[92:95], v[52:55]
	s_waitcnt lgkmcnt(0)
	v_mfma_f32_16x16x32_bf16 v[76:79], v[212:215], v[96:99], v[52:55]
	s_nop 4
	v_cndmask_b32_e64 v52, v105, v106, s[56:57]
	v_add_u32_e32 v60, v111, v52
	ds_read_b128 v[52:55], v60
	ds_read_b128 v[56:59], v60 offset:64
	ds_read_b128 v[208:211], v60 offset:128
	ds_read_b128 v[212:215], v60 offset:192
	s_waitcnt lgkmcnt(3)
	v_mfma_f32_16x16x32_bf16 v[52:55], v[52:55], v[48:51], 0
	v_readlane_b32 s56, v254, 49
	v_readlane_b32 s57, v254, 50
	s_waitcnt lgkmcnt(2)
	v_mfma_f32_16x16x32_bf16 v[52:55], v[56:59], v[88:91], v[52:55]
	s_waitcnt lgkmcnt(1)
	v_mfma_f32_16x16x32_bf16 v[52:55], v[208:211], v[92:95], v[52:55]
	s_waitcnt lgkmcnt(0)
	v_mfma_f32_16x16x32_bf16 v[72:75], v[212:215], v[96:99], v[52:55]
	s_nop 4
	v_cndmask_b32_e64 v52, v105, v106, s[44:45]
	v_add_u32_e32 v60, v189, v52
	ds_read_b128 v[52:55], v60
	ds_read_b128 v[56:59], v60 offset:64
	ds_read_b128 v[208:211], v60 offset:128
	ds_read_b128 v[212:215], v60 offset:192
	s_waitcnt lgkmcnt(3)
	v_mfma_f32_16x16x32_bf16 v[52:55], v[52:55], v[48:51], 0
	s_waitcnt lgkmcnt(2)
	v_mfma_f32_16x16x32_bf16 v[52:55], v[56:59], v[88:91], v[52:55]
	s_waitcnt lgkmcnt(1)
	v_mfma_f32_16x16x32_bf16 v[52:55], v[208:211], v[92:95], v[52:55]
	s_waitcnt lgkmcnt(0)
	v_mfma_f32_16x16x32_bf16 v[68:71], v[212:215], v[96:99], v[52:55]
	s_nop 4
	v_cndmask_b32_e64 v52, v105, v106, s[56:57]
	v_add_u32_e32 v60, v190, v52
	ds_read_b128 v[52:55], v60
	ds_read_b128 v[56:59], v60 offset:64
	ds_read_b128 v[208:211], v60 offset:128
	ds_read_b128 v[212:215], v60 offset:192
	s_waitcnt lgkmcnt(3)
	v_mfma_f32_16x16x32_bf16 v[52:55], v[52:55], v[48:51], 0
	v_readlane_b32 s56, v254, 51
	v_readlane_b32 s57, v254, 52
	s_waitcnt lgkmcnt(2)
	v_mfma_f32_16x16x32_bf16 v[52:55], v[56:59], v[88:91], v[52:55]
	s_waitcnt lgkmcnt(1)
	v_mfma_f32_16x16x32_bf16 v[52:55], v[208:211], v[92:95], v[52:55]
	v_add_u32_e32 v60, v191, v107
	v_add_u32_e32 v107, v192, v107
	s_waitcnt lgkmcnt(0)
	v_mfma_f32_16x16x32_bf16 v[64:67], v[212:215], v[96:99], v[52:55]
	s_nop 2
	ds_read_b128 v[52:55], v60
	ds_read_b128 v[56:59], v60 offset:64
	ds_read_b128 v[208:211], v60 offset:128
	ds_read_b128 v[212:215], v60 offset:192
	s_waitcnt lgkmcnt(3)
	v_mfma_f32_16x16x32_bf16 v[52:55], v[52:55], v[48:51], 0
	s_waitcnt lgkmcnt(2)
	v_mfma_f32_16x16x32_bf16 v[52:55], v[56:59], v[88:91], v[52:55]
	s_waitcnt lgkmcnt(1)
	v_mfma_f32_16x16x32_bf16 v[52:55], v[208:211], v[92:95], v[52:55]
	s_waitcnt lgkmcnt(0)
	v_mfma_f32_16x16x32_bf16 v[60:63], v[212:215], v[96:99], v[52:55]
	s_nop 4
	ds_read_b128 v[52:55], v107
	ds_read_b128 v[56:59], v107 offset:64
	ds_read_b128 v[208:211], v107 offset:128
	ds_read_b128 v[212:215], v107 offset:192
	s_waitcnt lgkmcnt(3)
	v_mfma_f32_16x16x32_bf16 v[52:55], v[52:55], v[48:51], 0
	s_waitcnt lgkmcnt(2)
	v_mfma_f32_16x16x32_bf16 v[52:55], v[56:59], v[88:91], v[52:55]
	s_waitcnt lgkmcnt(1)
	v_mfma_f32_16x16x32_bf16 v[52:55], v[208:211], v[92:95], v[52:55]
	s_waitcnt lgkmcnt(0)
	v_mfma_f32_16x16x32_bf16 v[56:59], v[212:215], v[96:99], v[52:55]
	s_nop 4
	v_cndmask_b32_e64 v52, v105, v106, s[50:51]
	v_add_u32_e32 v107, v193, v52
	ds_read_b128 v[52:55], v107
	ds_read_b128 v[122:125], v107 offset:64
	ds_read_b128 v[208:211], v107 offset:128
	ds_read_b128 v[212:215], v107 offset:192
	s_waitcnt lgkmcnt(3)
	v_mfma_f32_16x16x32_bf16 v[52:55], v[52:55], v[48:51], 0
	v_cndmask_b32_e64 v105, v105, v106, s[56:57]
	v_add_u32_e32 v105, v194, v105
	v_readlane_b32 s56, v254, 53
	s_waitcnt lgkmcnt(2)
	v_mfma_f32_16x16x32_bf16 v[52:55], v[122:125], v[88:91], v[52:55]
	v_readlane_b32 s57, v254, 54
	s_and_b64 vcc, s[56:57], vcc
	s_waitcnt lgkmcnt(1)
; #define LAS __attribute__((address_space(3)))
; __device__ __forceinline__ void attn_phase(const Params& p, LAS unsigned char* lds, int l, int mode) {
;     ...
;                 const int kb = kb0 + i, koff = (kb < 8) ? koffP + kb * (16 * 272) : koffC + (kb - 8) * (16 * 272);
; #pragma unroll
;                 for (int s = 0; s < 4; ++s) {
;                     const bf16x8 kf = *(const LAS bf16x8*)(Kl + koff + li * 272 + (32 * s + 8 * g) * 2);
;                     sacc[i] = __builtin_amdgcn_mfma_f32_16x16x32_bf16(kf, qc[s], sacc[i], 0, 0, 0);
;                 }
;             }
;             float mx = -1e30f;
; #pragma unroll
;             for (int i = 0; i < 10; ++i)
; #pragma unroll
;                 for (int j = 0; j < 4; ++j) {
;                     const int kj = 16 * (kb0 + i) + 4 * g + j, dist = 128 + qi - kj;
;                     const bool valid = (dist >= 0) && (dist <= 128) && (mbase + kj >= 0);
;                     const float sv = valid ? sacc[i][j] : -1e30f;
;                     sacc[i][j] = sv; mx = fmaxf(mx, sv);
;                 }
;             mx = fmaxf(mx, __shfl_xor(mx, 16)); mx = fmaxf(mx, __shfl_xor(mx, 32));
	v_mfma_f32_16x16x32_bf16 v[52:55], v[208:211], v[92:95], v[52:55]
	v_readlane_b32 s56, v254, 55
	v_cndmask_b32_e32 v84, v225, v84, vcc
	s_waitcnt lgkmcnt(0)
	v_mfma_f32_16x16x32_bf16 v[52:55], v[212:215], v[96:99], v[52:55]
	ds_read_b128 v[122:125], v105
	v_cmp_le_i32_e32 vcc, s43, v159
	v_readlane_b32 s57, v254, 56
	s_waitcnt lgkmcnt(0)
	v_mfma_f32_16x16x32_bf16 v[48:51], v[122:125], v[48:51], 0
	ds_read_b128 v[122:125], v105 offset:64
	ds_read_b128 v[208:211], v105 offset:128
	ds_read_b128 v[212:215], v105 offset:192
	s_and_b64 vcc, s[56:57], vcc
	v_cndmask_b32_e32 v85, v225, v85, vcc
	s_waitcnt lgkmcnt(2)
	v_mfma_f32_16x16x32_bf16 v[48:51], v[122:125], v[88:91], v[48:51]
	s_mov_b32 s56, 0xf149f2ca
	v_cmp_lt_i32_e32 vcc, s43, v160
	s_waitcnt lgkmcnt(1)
	v_mfma_f32_16x16x32_bf16 v[48:51], v[208:211], v[92:95], v[48:51]
	v_ashrrev_i32_e32 v105, 31, v104
	s_waitcnt lgkmcnt(0)
	v_mfma_f32_16x16x32_bf16 v[48:51], v[212:215], v[96:99], v[48:51]
	v_max3_f32 v90, v84, s56, v85
	v_readlane_b32 s56, v254, 57
	v_readlane_b32 s57, v254, 58
	s_and_b64 vcc, s[56:57], vcc
	v_cndmask_b32_e32 v86, v225, v86, vcc
	v_cmp_lt_i32_e32 vcc, s43, v161
	s_and_b64 vcc, s[60:61], vcc
	v_lshl_add_u64 v[88:89], s[2:3], 0, v[104:105]
	v_cndmask_b32_e32 v87, v225, v87, vcc
	v_cmp_lt_i32_e32 vcc, s43, v162
	s_and_b64 vcc, s[62:63], vcc
	v_max3_f32 v90, v90, v86, v87
	v_cndmask_b32_e32 v80, v225, v80, vcc
	v_cmp_le_i32_e32 vcc, s43, v162
	s_and_b64 vcc, s[64:65], vcc
	v_readlane_b32 s56, v252, 63
	v_cndmask_b32_e32 v81, v225, v81, vcc
	v_cmp_lt_i32_e32 vcc, s43, v163
	s_and_b64 vcc, s[66:67], vcc
	v_max3_f32 v90, v90, v80, v81
	v_cndmask_b32_e32 v82, v225, v82, vcc
	v_cmp_lt_i32_e32 vcc, s43, v164
	s_and_b64 vcc, s[68:69], vcc
	v_readlane_b32 s57, v253, 0
	v_cndmask_b32_e32 v83, v225, v83, vcc
	v_cmp_lt_i32_e32 vcc, s43, v165
	s_and_b64 vcc, s[70:71], vcc
	v_max3_f32 v90, v90, v82, v83
	v_cndmask_b32_e32 v76, v225, v76, vcc
	v_cmp_le_i32_e32 vcc, s43, v165
	s_and_b64 vcc, s[72:73], vcc
	s_nop 0
	v_cndmask_b32_e32 v77, v225, v77, vcc
	v_cmp_lt_i32_e32 vcc, s43, v166
	s_and_b64 vcc, s[74:75], vcc
	v_max3_f32 v90, v90, v76, v77
	v_cndmask_b32_e32 v78, v225, v78, vcc
	v_cmp_lt_i32_e32 vcc, s43, v167
	s_and_b64 vcc, s[76:77], vcc
	s_nop 0
	v_cndmask_b32_e32 v79, v225, v79, vcc
	v_cmp_lt_i32_e32 vcc, s43, v168
	s_and_b64 vcc, s[78:79], vcc
	v_max3_f32 v90, v90, v78, v79
	v_cndmask_b32_e32 v72, v225, v72, vcc
	v_cmp_le_i32_e32 vcc, s43, v168
	s_and_b64 vcc, s[80:81], vcc
	s_nop 0
	v_cndmask_b32_e32 v73, v225, v73, vcc
	v_cmp_lt_i32_e32 vcc, s43, v169
	s_and_b64 vcc, s[82:83], vcc
	v_max3_f32 v90, v90, v72, v73
	v_cndmask_b32_e32 v74, v225, v74, vcc
	v_cmp_lt_i32_e32 vcc, s43, v170
	s_and_b64 vcc, s[84:85], vcc
	s_nop 0
	v_cndmask_b32_e32 v75, v225, v75, vcc
	v_cmp_lt_i32_e32 vcc, s43, v171
	s_and_b64 vcc, s[86:87], vcc
	v_max3_f32 v90, v90, v74, v75
	v_cndmask_b32_e32 v68, v225, v68, vcc
	v_cmp_le_i32_e32 vcc, s43, v171
	s_and_b64 vcc, s[88:89], vcc
	s_nop 0
	v_cndmask_b32_e32 v69, v225, v69, vcc
	v_cmp_lt_i32_e32 vcc, s43, v172
	s_and_b64 vcc, s[90:91], vcc
	v_max3_f32 v90, v90, v68, v69
	v_cndmask_b32_e32 v70, v225, v70, vcc
	v_cmp_lt_i32_e32 vcc, s43, v173
	s_and_b64 vcc, s[92:93], vcc
	s_nop 0
	v_cndmask_b32_e32 v71, v225, v71, vcc
	v_cmp_lt_i32_e32 vcc, s43, v174
	s_and_b64 vcc, s[94:95], vcc
	v_max3_f32 v90, v90, v70, v71
	v_cndmask_b32_e32 v64, v225, v64, vcc
	v_cmp_le_i32_e32 vcc, s43, v174
	s_and_b64 vcc, s[96:97], vcc
	s_nop 0
	v_cndmask_b32_e32 v65, v225, v65, vcc
	v_cmp_lt_i32_e32 vcc, s43, v175
	s_and_b64 vcc, s[98:99], vcc
	v_max3_f32 v90, v90, v64, v65
	v_cndmask_b32_e32 v66, v225, v66, vcc
	v_cmp_lt_i32_e32 vcc, s43, v176
	s_and_b64 vcc, s[0:1], vcc
	s_nop 0
	v_cndmask_b32_e32 v67, v225, v67, vcc
	v_cmp_lt_i32_e32 vcc, s43, v177
	s_and_b64 vcc, s[38:39], vcc
	v_max3_f32 v90, v90, v66, v67
	v_cndmask_b32_e32 v60, v225, v60, vcc
	v_cmp_le_i32_e32 vcc, s43, v177
	s_and_b64 vcc, s[4:5], vcc
	s_nop 0
	v_cndmask_b32_e32 v61, v225, v61, vcc
	v_cmp_lt_i32_e32 vcc, s43, v178
	s_and_b64 vcc, s[6:7], vcc
	v_max3_f32 v90, v90, v60, v61
	v_cndmask_b32_e32 v62, v225, v62, vcc
	v_cmp_lt_i32_e32 vcc, s43, v179
	s_and_b64 vcc, s[8:9], vcc
	s_nop 0
	v_cndmask_b32_e32 v63, v225, v63, vcc
	v_cmp_lt_i32_e32 vcc, s43, v180
	s_and_b64 vcc, s[10:11], vcc
	v_max3_f32 v90, v90, v62, v63
	v_cndmask_b32_e32 v56, v225, v56, vcc
	v_cmp_le_i32_e32 vcc, s43, v180
	s_and_b64 vcc, s[12:13], vcc
	s_nop 0
	v_cndmask_b32_e32 v57, v225, v57, vcc
	v_cmp_lt_i32_e32 vcc, s43, v181
	s_and_b64 vcc, s[14:15], vcc
	v_max3_f32 v90, v90, v56, v57
	v_cndmask_b32_e32 v58, v225, v58, vcc
	v_cmp_lt_i32_e32 vcc, s43, v182
	s_and_b64 vcc, s[16:17], vcc
	s_nop 0
	v_cndmask_b32_e32 v59, v225, v59, vcc
	v_cmp_lt_i32_e32 vcc, s43, v183
	s_and_b64 vcc, s[18:19], vcc
	v_max3_f32 v90, v90, v58, v59
	v_cndmask_b32_e32 v52, v225, v52, vcc
	v_cmp_le_i32_e32 vcc, s43, v183
	s_and_b64 vcc, s[20:21], vcc
	s_nop 0
	v_cndmask_b32_e32 v53, v225, v53, vcc
	v_cmp_lt_i32_e32 vcc, s43, v184
	s_and_b64 vcc, s[22:23], vcc
	v_max3_f32 v90, v90, v52, v53
	v_cndmask_b32_e32 v54, v225, v54, vcc
	v_cmp_lt_i32_e32 vcc, s43, v185
	s_and_b64 vcc, s[24:25], vcc
	s_nop 0
	v_cndmask_b32_e32 v55, v225, v55, vcc
	v_cmp_lt_i32_e32 vcc, s43, v186
	s_and_b64 vcc, s[26:27], vcc
	v_max3_f32 v90, v90, v54, v55
	v_cndmask_b32_e32 v91, v225, v48, vcc
	v_cmp_le_i32_e32 vcc, s43, v186
	s_and_b64 vcc, s[28:29], vcc
	s_nop 0
	v_cndmask_b32_e32 v92, v225, v49, vcc
	v_cmp_lt_i32_e32 vcc, s43, v187
	s_and_b64 vcc, s[30:31], vcc
	v_max3_f32 v48, v90, v91, v92
	v_cndmask_b32_e32 v90, v225, v50, vcc
	v_cmp_lt_i32_e32 vcc, s43, v188
	v_and_b32_e32 v50, 64, v223
	s_and_b64 vcc, s[34:35], vcc
	v_xor_b32_e32 v49, 16, v223
	v_add_u32_e32 v50, 64, v50
	v_cndmask_b32_e32 v93, v225, v51, vcc
	v_cmp_lt_i32_e32 vcc, v49, v50
	v_max3_f32 v48, v48, v90, v93
	s_mov_b32 s43, 0x80000
	v_cndmask_b32_e32 v49, v223, v49, vcc
	v_lshlrev_b32_e32 v152, 2, v49
	ds_bpermute_b32 v49, v152, v48
	s_waitcnt lgkmcnt(0)
; #define LAS __attribute__((address_space(3)))
; __device__ __forceinline__ unsigned cvt_pk_bf16(float lo, float hi) { unsigned r; asm volatile("v_cvt_pk_bf16_f32 %0, %1, %2" : "=v"(r) : "v"(lo), "v"(hi)); return r; }
; __device__ __forceinline__ void attn_phase(const Params& p, LAS unsigned char* lds, int l, int mode) {
;     ...
;             mx = fmaxf(mx, __shfl_xor(mx, 16)); mx = fmaxf(mx, __shfl_xor(mx, 32));
;             float lsum = 0.f;
; #pragma unroll
;             for (int i = 0; i < 10; ++i)
; #pragma unroll
;                 for (int j = 0; j < 4; ++j) { const float pv = __builtin_amdgcn_exp2f(sacc[i][j] - mx); sacc[i][j] = pv; lsum += pv; }
;             lsum += __shfl_xor(lsum, 16); lsum += __shfl_xor(lsum, 32);
;             u32x2 x1[8], x2[8]; float l1 = 0.f, l2 = 0.f;
;             if (mode) {
;                 l1 = lse[qtok * 8 + h]; l2 = lse[((size_t)T_TOK + qtok) * 8 + h];
;                 const bf16_t* p1 = opart + qtok * 1024 + h * 128 + 4 * g; const bf16_t* p2 = p1 + (size_t)T_TOK * 1024;
; #pragma unroll
;                 for (int db = 0; db < 8; ++db) { x1[db] = *(const u32x2*)(p1 + 16 * db); x2[db] = *(const u32x2*)(p2 + 16 * db); }
;             }
;             f32x4 oacc[8];
; #pragma unroll
;             for (int db = 0; db < 8; ++db) oacc[db] = (f32x4){0.f, 0.f, 0.f, 0.f};
;             const int vlane = (4 * g + (li >> 2)) * 288 + (4 * (li & 3)) * 2;
; #pragma unroll
;             for (int t = 0; t < 5; ++t) {
;                 u32x4 pw; pw.x = cvt_pk_bf16(sacc[2 * t][0], sacc[2 * t][1]); pw.y = cvt_pk_bf16(sacc[2 * t][2], sacc[2 * t][3]);
;                 pw.z = cvt_pk_bf16(sacc[2 * t + 1][0], sacc[2 * t + 1][1]); pw.w = cvt_pk_bf16(sacc[2 * t + 1][2], sacc[2 * t + 1][3]);
;                 const bf16x8 pf = __builtin_bit_cast(bf16x8, pw);
;                 const int kbv = kb0 + 2 * t, voff = (kbv < 8) ? voffP + kbv * (16 * 288) : voffC + (kbv - 8) * (16 * 288);
;                 const LAS unsigned char* vb = Vl + voff + vlane;
; #pragma unroll
;                 for (int db = 0; db < 8; ++db) {
;                     const s16x4 lo = __builtin_bit_cast(s16x4, __builtin_amdgcn_ds_read_tr16_b64_v4i16((LAS s16x4*)(vb + db * 32)));
	v_max_f32_e32 v49, v49, v49
	v_max_f32_e32 v48, v48, v49
	v_xor_b32_e32 v49, 32, v223
	v_cmp_lt_i32_e32 vcc, v49, v50
	s_nop 1
	v_cndmask_b32_e32 v49, v223, v49, vcc
	v_lshlrev_b32_e32 v200, 2, v49
	ds_bpermute_b32 v49, v200, v48
	s_waitcnt lgkmcnt(0)
	v_max_f32_e32 v49, v49, v49
	v_max_f32_e32 v136, v48, v49
	v_sub_f32_e32 v48, v84, v136
	v_exp_f32_e32 v48, v48
	v_sub_f32_e32 v49, v85, v136
	v_exp_f32_e32 v49, v49
	v_sub_f32_e32 v80, v80, v136
	v_add_f32_e32 v50, 0, v48
	v_exp_f32_e32 v206, v80
	v_add_f32_e32 v51, v49, v50
	v_sub_f32_e32 v50, v86, v136
	v_exp_f32_e32 v50, v50
	v_sub_f32_e32 v81, v81, v136
	v_exp_f32_e32 v207, v81
	v_sub_f32_e32 v81, v82, v136
	v_add_f32_e32 v84, v50, v51
	v_sub_f32_e32 v51, v87, v136
	v_exp_f32_e32 v51, v51
	v_exp_f32_e32 v208, v81
	v_sub_f32_e32 v81, v83, v136
	v_exp_f32_e32 v209, v81
	v_add_f32_e32 v84, v51, v84
	v_sub_f32_e32 v76, v76, v136
	v_add_f32_e32 v80, v206, v84
	v_exp_f32_e32 v76, v76
	v_sub_f32_e32 v77, v77, v136
	v_add_f32_e32 v80, v207, v80
	v_exp_f32_e32 v77, v77
	v_sub_f32_e32 v78, v78, v136
	v_add_f32_e32 v80, v208, v80
	v_exp_f32_e32 v78, v78
	v_sub_f32_e32 v79, v79, v136
	v_add_f32_e32 v80, v209, v80
	v_exp_f32_e32 v79, v79
	v_sub_f32_e32 v72, v72, v136
	v_add_f32_e32 v80, v76, v80
	v_exp_f32_e32 v202, v72
	v_sub_f32_e32 v73, v73, v136
	v_add_f32_e32 v80, v77, v80
	v_exp_f32_e32 v203, v73
	v_sub_f32_e32 v73, v74, v136
	v_add_f32_e32 v80, v78, v80
	v_exp_f32_e32 v204, v73
	v_sub_f32_e32 v73, v75, v136
	v_add_f32_e32 v80, v79, v80
	v_exp_f32_e32 v205, v73
	v_sub_f32_e32 v68, v68, v136
	v_add_f32_e32 v72, v202, v80
	v_exp_f32_e32 v68, v68
	v_sub_f32_e32 v69, v69, v136
	v_add_f32_e32 v72, v203, v72
	v_exp_f32_e32 v69, v69
	v_sub_f32_e32 v70, v70, v136
	v_add_f32_e32 v72, v204, v72
	v_exp_f32_e32 v70, v70
	v_sub_f32_e32 v71, v71, v136
	v_add_f32_e32 v72, v205, v72
	v_exp_f32_e32 v71, v71
	v_add_f32_e32 v72, v68, v72
	v_add_f32_e32 v72, v69, v72
	v_add_f32_e32 v72, v70, v72
	v_sub_f32_e32 v64, v64, v136
	v_add_f32_e32 v73, v71, v72
	v_exp_f32_e32 v72, v64
	v_sub_f32_e32 v65, v65, v136
	v_sub_f32_e32 v60, v60, v136
	v_exp_f32_e32 v60, v60
	v_add_f32_e32 v64, v72, v73
	v_exp_f32_e32 v73, v65
	v_sub_f32_e32 v65, v66, v136
	v_exp_f32_e32 v74, v65
	v_sub_f32_e32 v65, v67, v136
	v_exp_f32_e32 v75, v65
	v_sub_f32_e32 v61, v61, v136
	v_add_f32_e32 v64, v73, v64
	v_exp_f32_e32 v61, v61
	v_sub_f32_e32 v62, v62, v136
	v_add_f32_e32 v64, v74, v64
	v_exp_f32_e32 v62, v62
	v_sub_f32_e32 v63, v63, v136
	v_add_f32_e32 v64, v75, v64
	v_exp_f32_e32 v63, v63
	v_add_f32_e32 v64, v60, v64
	v_add_f32_e32 v64, v61, v64
	v_add_f32_e32 v64, v62, v64
	v_sub_f32_e32 v56, v56, v136
	v_add_f32_e32 v65, v63, v64
	v_exp_f32_e32 v64, v56
	v_sub_f32_e32 v57, v57, v136
	v_sub_f32_e32 v52, v52, v136
	v_exp_f32_e32 v52, v52
	v_add_f32_e32 v56, v64, v65
	v_exp_f32_e32 v65, v57
	v_sub_f32_e32 v57, v58, v136
	v_exp_f32_e32 v66, v57
	v_sub_f32_e32 v57, v59, v136
	v_exp_f32_e32 v67, v57
	v_sub_f32_e32 v53, v53, v136
	v_add_f32_e32 v56, v65, v56
	v_exp_f32_e32 v53, v53
	v_sub_f32_e32 v54, v54, v136
	v_add_f32_e32 v56, v66, v56
	v_exp_f32_e32 v54, v54
	v_sub_f32_e32 v55, v55, v136
	v_add_f32_e32 v56, v67, v56
	v_exp_f32_e32 v55, v55
	v_add_f32_e32 v56, v52, v56
	v_add_f32_e32 v56, v53, v56
	v_add_f32_e32 v56, v54, v56
	v_add_f32_e32 v57, v55, v56
	v_sub_f32_e32 v56, v91, v136
	v_exp_f32_e32 v56, v56
	s_nop 0
	v_add_f32_e32 v58, v56, v57
	v_sub_f32_e32 v57, v92, v136
	v_exp_f32_e32 v57, v57
	s_nop 0
	v_add_f32_e32 v59, v57, v58
	v_sub_f32_e32 v58, v90, v136
	v_exp_f32_e32 v58, v58
	s_nop 0
	v_add_f32_e32 v80, v58, v59
	v_sub_f32_e32 v59, v93, v136
	v_exp_f32_e32 v59, v59
	s_nop 0
	v_add_f32_e32 v80, v59, v80
	ds_bpermute_b32 v81, v152, v80
	s_waitcnt lgkmcnt(0)
	v_add_f32_e32 v80, v80, v81
	ds_bpermute_b32 v81, v200, v80
	s_waitcnt lgkmcnt(0)
	v_add_f32_e32 v138, v80, v81
	v_lshlrev_b64 v[80:81], 5, v[88:89]
	v_lshl_add_u64 v[80:81], s[56:57], 0, v[80:81]
	v_lshl_add_u64 v[80:81], v[80:81], 0, s[52:53]
	global_load_dword v139, v[80:81], off
	v_add_co_u32_e32 v80, vcc, s43, v80
	s_brev_b32 s43, 64
	s_nop 0
	v_addc_co_u32_e32 v81, vcc, 0, v81, vcc
	global_load_dword v201, v[80:81], off
	v_lshlrev_b64 v[80:81], 11, v[88:89]
	v_lshl_add_u64 v[80:81], v[118:119], 0, v[80:81]
	v_add_co_u32_e32 v82, vcc, s43, v80
	s_add_i32 s43, s55, 0xffff7000
	s_nop 0
	v_addc_co_u32_e32 v83, vcc, 0, v81, vcc
	global_load_dwordx2 v[132:133], v[80:81], off
	global_load_dwordx2 v[134:135], v[82:83], off
	global_load_dwordx2 v[128:129], v[80:81], off offset:32
	global_load_dwordx2 v[130:131], v[82:83], off offset:32
	global_load_dwordx2 v[124:125], v[80:81], off offset:64
	global_load_dwordx2 v[126:127], v[82:83], off offset:64
	global_load_dwordx2 v[98:99], v[80:81], off offset:96
	global_load_dwordx2 v[122:123], v[82:83], off offset:96
	global_load_dwordx2 v[94:95], v[80:81], off offset:128
	global_load_dwordx2 v[96:97], v[82:83], off offset:128
	global_load_dwordx2 v[90:91], v[80:81], off offset:160
	global_load_dwordx2 v[92:93], v[82:83], off offset:160
	global_load_dwordx2 v[84:85], v[80:81], off offset:192
	global_load_dwordx2 v[86:87], v[82:83], off offset:192
	s_nop 0
	global_load_dwordx2 v[80:81], v[80:81], off offset:224
	s_nop 0
	global_load_dwordx2 v[82:83], v[82:83], off offset:224
	v_cvt_pk_bf16_f32 v48, v48, v49
	v_cvt_pk_bf16_f32 v49, v50, v51
	v_cvt_pk_bf16_f32 v50, v206, v207
	v_mov_b32_e32 v89, s43
	v_mov_b32_e32 v206, s42
	v_cndmask_b32_e64 v104, v89, v206, s[36:37]
	v_add_u32_e32 v106, v103, v104
	v_cvt_pk_bf16_f32 v51, v208, v209
	ds_read_b64_tr_b16 v[210:211], v106 offset:4608
	ds_read_b64_tr_b16 v[208:209], v106
	ds_read_b64_tr_b16 v[212:213], v106 offset:32
	ds_read_b64_tr_b16 v[214:215], v106 offset:4640
	ds_read_b64_tr_b16 v[216:217], v106 offset:64
	ds_read_b64_tr_b16 v[218:219], v106 offset:4672
	ds_read_b64_tr_b16 v[228:229], v106 offset:96
	ds_read_b64_tr_b16 v[230:231], v106 offset:4704
	ds_read_b64_tr_b16 v[232:233], v106 offset:128
	ds_read_b64_tr_b16 v[234:235], v106 offset:4736
	ds_read_b64_tr_b16 v[242:243], v106 offset:160
	ds_read_b64_tr_b16 v[244:245], v106 offset:4768
	ds_read_b64_tr_b16 v[246:247], v106 offset:192
	ds_read_b64_tr_b16 v[248:249], v106 offset:4800
	ds_read_b64_tr_b16 v[104:105], v106 offset:224
	ds_read_b64_tr_b16 v[106:107], v106 offset:4832
	s_waitcnt lgkmcnt(14)
; #define LAS __attribute__((address_space(3)))
; __device__ __forceinline__ unsigned cvt_pk_bf16(float lo, float hi) { unsigned r; asm volatile("v_cvt_pk_bf16_f32 %0, %1, %2" : "=v"(r) : "v"(lo), "v"(hi)); return r; }
; __device__ __forceinline__ void attn_phase(const Params& p, LAS unsigned char* lds, int l, int mode) {
;     ...
; #pragma unroll
;             for (int t = 0; t < 5; ++t) {
;                 u32x4 pw; pw.x = cvt_pk_bf16(sacc[2 * t][0], sacc[2 * t][1]); pw.y = cvt_pk_bf16(sacc[2 * t][2], sacc[2 * t][3]);
;                 pw.z = cvt_pk_bf16(sacc[2 * t + 1][0], sacc[2 * t + 1][1]); pw.w = cvt_pk_bf16(sacc[2 * t + 1][2], sacc[2 * t + 1][3]);
;                 const bf16x8 pf = __builtin_bit_cast(bf16x8, pw);
;                 const int kbv = kb0 + 2 * t, voff = (kbv < 8) ? voffP + kbv * (16 * 288) : voffC + (kbv - 8) * (16 * 288);
;                 const LAS unsigned char* vb = Vl + voff + vlane;
; #pragma unroll
;                 for (int db = 0; db < 8; ++db) {
;                     const s16x4 lo = __builtin_bit_cast(s16x4, __builtin_amdgcn_ds_read_tr16_b64_v4i16((LAS s16x4*)(vb + db * 32)));
;                     const s16x4 hi = __builtin_bit_cast(s16x4, __builtin_amdgcn_ds_read_tr16_b64_v4i16((LAS s16x4*)(vb + 16 * 288 + db * 32)));
;                     const bf16x8 vf = __builtin_shufflevector(lo, hi, 0, 1, 2, 3, 4, 5, 6, 7);
;                     oacc[db] = __builtin_amdgcn_mfma_f32_16x16x32_bf16(vf, pf, oacc[db], 0, 0, 0);
;                 }
;             }
	v_mfma_f32_16x16x32_bf16 v[208:211], v[208:211], v[48:51], 0
	v_cvt_pk_bf16_f32 v76, v76, v77
	v_cvt_pk_bf16_f32 v77, v78, v79
	v_cvt_pk_bf16_f32 v78, v202, v203
	s_waitcnt lgkmcnt(12)
	v_mfma_f32_16x16x32_bf16 v[212:215], v[212:215], v[48:51], 0
	v_cvt_pk_bf16_f32 v79, v204, v205
	s_cmp_eq_u32 s47, 4
	s_waitcnt lgkmcnt(10)
	v_mfma_f32_16x16x32_bf16 v[216:219], v[216:219], v[48:51], 0
	s_waitcnt lgkmcnt(8)
	v_mfma_f32_16x16x32_bf16 v[228:231], v[228:231], v[48:51], 0
	s_waitcnt lgkmcnt(6)
	v_mfma_f32_16x16x32_bf16 v[232:235], v[232:235], v[48:51], 0
	s_waitcnt lgkmcnt(4)
	v_mfma_f32_16x16x32_bf16 v[242:245], v[242:245], v[48:51], 0
	s_waitcnt lgkmcnt(2)
	v_mfma_f32_16x16x32_bf16 v[246:249], v[246:249], v[48:51], 0
	s_waitcnt lgkmcnt(0)
	v_mfma_f32_16x16x32_bf16 v[48:51], v[104:107], v[48:51], 0
	v_cndmask_b32_e64 v104, v89, v206, s[40:41]
	v_add_u32_e32 v207, v195, v104
	ds_read_b64_tr_b16 v[106:107], v207 offset:4608
	ds_read_b64_tr_b16 v[104:105], v207
	ds_read_b64_tr_b16 v[202:203], v207 offset:32
	ds_read_b64_tr_b16 v[204:205], v207 offset:4640
	s_waitcnt lgkmcnt(2)
	v_mfma_f32_16x16x32_bf16 v[104:107], v[104:107], v[76:79], v[208:211]
	s_nop 2
	ds_read_b64_tr_b16 v[208:209], v207 offset:64
	ds_read_b64_tr_b16 v[210:211], v207 offset:4672
	s_waitcnt lgkmcnt(2)
	v_mfma_f32_16x16x32_bf16 v[202:205], v[202:205], v[76:79], v[212:215]
	s_nop 2
	ds_read_b64_tr_b16 v[212:213], v207 offset:96
	ds_read_b64_tr_b16 v[214:215], v207 offset:4704
	s_waitcnt lgkmcnt(2)
	v_mfma_f32_16x16x32_bf16 v[208:211], v[208:211], v[76:79], v[216:219]
	s_nop 2
	ds_read_b64_tr_b16 v[216:217], v207 offset:128
	ds_read_b64_tr_b16 v[218:219], v207 offset:4736
	s_waitcnt lgkmcnt(2)
	v_mfma_f32_16x16x32_bf16 v[212:215], v[212:215], v[76:79], v[228:231]
	s_nop 2
	ds_read_b64_tr_b16 v[228:229], v207 offset:160
	ds_read_b64_tr_b16 v[230:231], v207 offset:4768
	s_waitcnt lgkmcnt(2)
	v_mfma_f32_16x16x32_bf16 v[216:219], v[216:219], v[76:79], v[232:235]
	s_nop 2
	ds_read_b64_tr_b16 v[232:233], v207 offset:192
	ds_read_b64_tr_b16 v[234:235], v207 offset:4800
	s_waitcnt lgkmcnt(2)
	v_mfma_f32_16x16x32_bf16 v[228:231], v[228:231], v[76:79], v[242:245]
	s_nop 2
	ds_read_b64_tr_b16 v[242:243], v207 offset:224
	ds_read_b64_tr_b16 v[244:245], v207 offset:4832
	v_cvt_pk_bf16_f32 v68, v68, v69
	v_cvt_pk_bf16_f32 v69, v70, v71
	v_cvt_pk_bf16_f32 v70, v72, v73
	v_cndmask_b32_e64 v72, v89, v206, s[44:45]
	v_add_u32_e32 v207, v196, v72
	s_waitcnt lgkmcnt(2)
	v_mfma_f32_16x16x32_bf16 v[232:235], v[232:235], v[76:79], v[246:249]
	v_cvt_pk_bf16_f32 v71, v74, v75
	s_waitcnt lgkmcnt(0)
	v_mfma_f32_16x16x32_bf16 v[48:51], v[242:245], v[76:79], v[48:51]
	ds_read_b64_tr_b16 v[74:75], v207 offset:4608
	ds_read_b64_tr_b16 v[72:73], v207
	ds_read_b64_tr_b16 v[76:77], v207 offset:32
	ds_read_b64_tr_b16 v[78:79], v207 offset:4640
	s_waitcnt lgkmcnt(2)
	v_mfma_f32_16x16x32_bf16 v[72:75], v[72:75], v[68:71], v[104:107]
	s_nop 2
	ds_read_b64_tr_b16 v[104:105], v207 offset:64
	ds_read_b64_tr_b16 v[106:107], v207 offset:4672
	s_waitcnt lgkmcnt(2)
	v_mfma_f32_16x16x32_bf16 v[76:79], v[76:79], v[68:71], v[202:205]
	s_nop 2
	ds_read_b64_tr_b16 v[202:203], v207 offset:96
	ds_read_b64_tr_b16 v[204:205], v207 offset:4704
	s_waitcnt lgkmcnt(2)
	v_mfma_f32_16x16x32_bf16 v[104:107], v[104:107], v[68:71], v[208:211]
	s_nop 2
	ds_read_b64_tr_b16 v[208:209], v207 offset:128
	ds_read_b64_tr_b16 v[210:211], v207 offset:4736
	s_waitcnt lgkmcnt(2)
	v_mfma_f32_16x16x32_bf16 v[202:205], v[202:205], v[68:71], v[212:215]
	s_nop 2
	ds_read_b64_tr_b16 v[212:213], v207 offset:160
	ds_read_b64_tr_b16 v[214:215], v207 offset:4768
	s_waitcnt lgkmcnt(2)
	v_mfma_f32_16x16x32_bf16 v[208:211], v[208:211], v[68:71], v[216:219]
	s_nop 2
	ds_read_b64_tr_b16 v[216:217], v207 offset:192
	ds_read_b64_tr_b16 v[218:219], v207 offset:4800
	s_waitcnt lgkmcnt(2)
	v_mfma_f32_16x16x32_bf16 v[212:215], v[212:215], v[68:71], v[228:231]
	s_nop 2
	ds_read_b64_tr_b16 v[228:229], v207 offset:224
	ds_read_b64_tr_b16 v[230:231], v207 offset:4832
	v_cvt_pk_bf16_f32 v60, v60, v61
	v_cvt_pk_bf16_f32 v61, v62, v63
	v_cvt_pk_bf16_f32 v62, v64, v65
	v_cndmask_b32_e64 v64, v89, v206, s[48:49]
	v_add_u32_e32 v207, v197, v64
	s_waitcnt lgkmcnt(2)
	v_mfma_f32_16x16x32_bf16 v[216:219], v[216:219], v[68:71], v[232:235]
	v_cvt_pk_bf16_f32 v63, v66, v67
	s_waitcnt lgkmcnt(0)
	v_mfma_f32_16x16x32_bf16 v[48:51], v[228:231], v[68:71], v[48:51]
	ds_read_b64_tr_b16 v[66:67], v207 offset:4608
	ds_read_b64_tr_b16 v[64:65], v207
	ds_read_b64_tr_b16 v[68:69], v207 offset:32
	ds_read_b64_tr_b16 v[70:71], v207 offset:4640
	s_waitcnt lgkmcnt(2)
	v_mfma_f32_16x16x32_bf16 v[64:67], v[64:67], v[60:63], v[72:75]
	s_nop 2
	ds_read_b64_tr_b16 v[72:73], v207 offset:64
	ds_read_b64_tr_b16 v[74:75], v207 offset:4672
	s_waitcnt lgkmcnt(0)
	v_mfma_f32_16x16x32_bf16 v[104:107], v[72:75], v[60:63], v[104:107]
	ds_read_b64_tr_b16 v[72:73], v207 offset:96
	ds_read_b64_tr_b16 v[74:75], v207 offset:4704
	s_waitcnt lgkmcnt(0)
	v_mfma_f32_16x16x32_bf16 v[202:205], v[72:75], v[60:63], v[202:205]
	ds_read_b64_tr_b16 v[72:73], v207 offset:128
	ds_read_b64_tr_b16 v[74:75], v207 offset:4736
	s_waitcnt lgkmcnt(0)
	v_mfma_f32_16x16x32_bf16 v[208:211], v[72:75], v[60:63], v[208:211]
	ds_read_b64_tr_b16 v[72:73], v207 offset:160
	ds_read_b64_tr_b16 v[74:75], v207 offset:4768
	s_waitcnt lgkmcnt(0)
	v_mfma_f32_16x16x32_bf16 v[212:215], v[72:75], v[60:63], v[212:215]
	ds_read_b64_tr_b16 v[72:73], v207 offset:192
	ds_read_b64_tr_b16 v[74:75], v207 offset:4800
	s_waitcnt lgkmcnt(0)
; #define LAS __attribute__((address_space(3)))
; __device__ __forceinline__ unsigned cvt_pk_bf16(float lo, float hi) { unsigned r; asm volatile("v_cvt_pk_bf16_f32 %0, %1, %2" : "=v"(r) : "v"(lo), "v"(hi)); return r; }
; __device__ __forceinline__ float bflo(unsigned w) { return __uint_as_float(w << 16); }
; __device__ __forceinline__ float bfhi(unsigned w) { return __uint_as_float(w & 0xffff0000u); }
; __device__ __forceinline__ void attn_phase(const Params& p, LAS unsigned char* lds, int l, int mode) {
;     ...
;                     const s16x4 hi = __builtin_bit_cast(s16x4, __builtin_amdgcn_ds_read_tr16_b64_v4i16((LAS s16x4*)(vb + 16 * 288 + db * 32)));
;                     const bf16x8 vf = __builtin_shufflevector(lo, hi, 0, 1, 2, 3, 4, 5, 6, 7);
;                     oacc[db] = __builtin_amdgcn_mfma_f32_16x16x32_bf16(vf, pf, oacc[db], 0, 0, 0);
;                 }
;             }
;             const float inv = 1.0f / lsum, lse0 = mx + __builtin_amdgcn_logf(lsum);
;             if (mode == 0) {
;                 bf16_t* op = opart + ((size_t)(cur.br - 1) * T_TOK + qtok) * 1024 + h * 128 + 4 * g;
; #pragma unroll
;                 for (int db = 0; db < 8; ++db) { const f32x4 o = oacc[db] * inv; u32x2 w; w.x = cvt_pk_bf16(o[0], o[1]); w.y = cvt_pk_bf16(o[2], o[3]); *(u32x2*)(op + 16 * db) = w; }
;                 if (g == 0) lse[((size_t)(cur.br - 1) * T_TOK + qtok) * 8 + h] = lse0;
;             } else {
;                 const float lm = fmaxf(lse0, fmaxf(l1, l2));
;                 const float w0 = __builtin_amdgcn_exp2f(lse0 - lm), w1 = __builtin_amdgcn_exp2f(l1 - lm), w2 = __builtin_amdgcn_exp2f(l2 - lm);
;                 const float wi = 1.0f / (w0 + w1 + w2), a0 = w0 * wi * inv, a1 = w1 * wi, a2 = w2 * wi;
;                 float ss = 0.f;
; #pragma unroll
;                 for (int db = 0; db < 8; ++db) {
;                     f32x4 o = oacc[db] * a0;
;                     o[0] += bflo(x1[db].x) * a1 + bflo(x2[db].x) * a2; o[1] += bfhi(x1[db].x) * a1 + bfhi(x2[db].x) * a2;
;                     o[2] += bflo(x1[db].y) * a1 + bflo(x2[db].y) * a2; o[3] += bfhi(x1[db].y) * a1 + bfhi(x2[db].y) * a2;
;                     oacc[db] = o; ss += (o[0] * o[0] + o[1] * o[1]) + (o[2] * o[2] + o[3] * o[3]);
	v_mfma_f32_16x16x32_bf16 v[216:219], v[72:75], v[60:63], v[216:219]
	ds_read_b64_tr_b16 v[72:73], v207 offset:224
	ds_read_b64_tr_b16 v[74:75], v207 offset:4832
	v_cvt_pk_bf16_f32 v228, v52, v53
	v_cndmask_b32_e64 v52, v89, v206, s[50:51]
	v_add_u32_e32 v89, v198, v52
	v_cvt_pk_bf16_f32 v229, v54, v55
	v_cvt_pk_bf16_f32 v230, v56, v57
	v_cvt_pk_bf16_f32 v231, v58, v59
	ds_read_b64_tr_b16 v[54:55], v89 offset:4608
	ds_read_b64_tr_b16 v[52:53], v89
	ds_read_b64_tr_b16 v[56:57], v89 offset:32
	ds_read_b64_tr_b16 v[58:59], v89 offset:4640
	v_mfma_f32_16x16x32_bf16 v[68:71], v[68:71], v[60:63], v[76:79]
	s_waitcnt lgkmcnt(2)
	v_mfma_f32_16x16x32_bf16 v[76:79], v[52:55], v[228:231], v[64:67]
	ds_read_b64_tr_b16 v[52:53], v89 offset:64
	ds_read_b64_tr_b16 v[54:55], v89 offset:4672
	v_mfma_f32_16x16x32_bf16 v[48:51], v[72:75], v[60:63], v[48:51]
	s_waitcnt lgkmcnt(2)
	v_mfma_f32_16x16x32_bf16 v[72:75], v[56:59], v[228:231], v[68:71]
	s_waitcnt lgkmcnt(0)
	v_mfma_f32_16x16x32_bf16 v[68:71], v[52:55], v[228:231], v[104:107]
	ds_read_b64_tr_b16 v[52:53], v89 offset:96
	ds_read_b64_tr_b16 v[54:55], v89 offset:4704
	s_waitcnt lgkmcnt(0)
	v_mfma_f32_16x16x32_bf16 v[64:67], v[52:55], v[228:231], v[202:205]
	ds_read_b64_tr_b16 v[52:53], v89 offset:128
	ds_read_b64_tr_b16 v[54:55], v89 offset:4736
	s_waitcnt lgkmcnt(0)
	v_mfma_f32_16x16x32_bf16 v[60:63], v[52:55], v[228:231], v[208:211]
	ds_read_b64_tr_b16 v[52:53], v89 offset:160
	ds_read_b64_tr_b16 v[54:55], v89 offset:4768
	s_waitcnt lgkmcnt(0)
	v_mfma_f32_16x16x32_bf16 v[56:59], v[52:55], v[228:231], v[212:215]
	ds_read_b64_tr_b16 v[52:53], v89 offset:192
	ds_read_b64_tr_b16 v[54:55], v89 offset:4800
	ds_read_b64_tr_b16 v[104:105], v89 offset:224
	ds_read_b64_tr_b16 v[106:107], v89 offset:4832
	v_div_scale_f32 v89, s[42:43], v138, v138, 1.0
	s_waitcnt lgkmcnt(0)
	v_mfma_f32_16x16x32_bf16 v[48:51], v[104:107], v[228:231], v[48:51]
	v_rcp_f32_e32 v104, v89
	s_nop 0
	v_fma_f32 v105, -v89, v104, 1.0
	v_fmac_f32_e32 v104, v105, v104
	v_div_scale_f32 v105, vcc, 1.0, v138, 1.0
	v_mul_f32_e32 v106, v105, v104
	v_fma_f32 v107, -v89, v106, v105
	v_fmac_f32_e32 v106, v107, v104
	v_fma_f32 v89, -v89, v106, v105
	v_div_fmas_f32 v89, v89, v104, v106
	v_log_f32_e32 v104, v138
	v_div_fixup_f32 v89, v89, v138, 1.0
	v_mfma_f32_16x16x32_bf16 v[52:55], v[52:55], v[228:231], v[216:219]
	v_add_f32_e32 v104, v136, v104
	s_waitcnt vmcnt(16)
	v_max3_f32 v106, v104, v139, v201
	v_sub_f32_e32 v104, v104, v106
	v_exp_f32_e32 v107, v104
	v_sub_f32_e32 v104, v139, v106
	v_exp_f32_e32 v105, v104
	v_sub_f32_e32 v104, v201, v106
	v_exp_f32_e32 v104, v104
	v_add_f32_e32 v106, v107, v105
	v_add_f32_e32 v106, v104, v106
	v_div_scale_f32 v136, s[42:43], v106, v106, 1.0
	v_rcp_f32_e32 v138, v136
	s_mov_b32 s42, 0x800000
	v_fma_f32 v139, -v136, v138, 1.0
	v_fmac_f32_e32 v138, v139, v138
	v_div_scale_f32 v139, vcc, 1.0, v106, 1.0
	v_mul_f32_e32 v201, v139, v138
	v_fma_f32 v202, -v136, v201, v139
	v_fmac_f32_e32 v201, v202, v138
	v_fma_f32 v136, -v136, v201, v139
	v_div_fmas_f32 v136, v136, v138, v201
	v_div_fixup_f32 v106, v136, v106, 1.0
	v_mul_f32_e32 v107, v107, v106
	v_mul_f32_e32 v136, v89, v107
	v_pk_mul_f32 v[138:139], v[104:105], v[106:107] op_sel_hi:[1,0]
	s_waitcnt vmcnt(15)
	v_lshlrev_b32_e32 v106, 16, v132
	s_waitcnt vmcnt(14)
	v_and_b32_e32 v107, 0xffff0000, v134
	v_lshlrev_b32_e32 v104, 16, v134
	v_and_b32_e32 v105, 0xffff0000, v132
	v_pk_mul_f32 v[106:107], v[138:139], v[106:107] op_sel:[1,0] op_sel_hi:[0,1]
	v_pk_fma_f32 v[104:105], v[138:139], v[104:105], v[106:107]
	v_lshlrev_b32_e32 v106, 16, v133
	v_and_b32_e32 v107, 0xffff0000, v135
	v_pk_fma_f32 v[76:77], v[136:137], v[76:77], v[104:105] op_sel_hi:[0,1,1]
	v_lshlrev_b32_e32 v104, 16, v135
	v_and_b32_e32 v105, 0xffff0000, v133
	v_pk_mul_f32 v[106:107], v[138:139], v[106:107] op_sel:[1,0] op_sel_hi:[0,1]
	v_pk_fma_f32 v[104:105], v[138:139], v[104:105], v[106:107]
	s_waitcnt vmcnt(13)
	v_lshlrev_b32_e32 v106, 16, v128
	s_waitcnt vmcnt(12)
	v_and_b32_e32 v107, 0xffff0000, v130
	v_pk_fma_f32 v[78:79], v[136:137], v[78:79], v[104:105] op_sel_hi:[0,1,1]
	v_lshlrev_b32_e32 v104, 16, v130
	v_and_b32_e32 v105, 0xffff0000, v128
	v_pk_mul_f32 v[106:107], v[138:139], v[106:107] op_sel:[1,0] op_sel_hi:[0,1]
	v_pk_fma_f32 v[104:105], v[138:139], v[104:105], v[106:107]
	v_lshlrev_b32_e32 v106, 16, v129
	v_and_b32_e32 v107, 0xffff0000, v131
	v_pk_fma_f32 v[72:73], v[136:137], v[72:73], v[104:105] op_sel_hi:[0,1,1]
	v_lshlrev_b32_e32 v104, 16, v131
	v_and_b32_e32 v105, 0xffff0000, v129
	v_pk_mul_f32 v[106:107], v[138:139], v[106:107] op_sel:[1,0] op_sel_hi:[0,1]
	v_pk_fma_f32 v[104:105], v[138:139], v[104:105], v[106:107]
	v_mov_b32_e32 v106, v77
	v_pk_fma_f32 v[74:75], v[136:137], v[74:75], v[104:105] op_sel_hi:[0,1,1]
	v_mov_b32_e32 v107, v73
	v_mov_b32_e32 v104, v76
	v_mov_b32_e32 v105, v72
	v_pk_mul_f32 v[106:107], v[106:107], v[106:107]
	v_mov_b32_e32 v128, v79
	v_mov_b32_e32 v129, v75
	v_pk_fma_f32 v[104:105], v[104:105], v[104:105], v[106:107]
	v_mov_b32_e32 v106, v78
	v_mov_b32_e32 v107, v74
	v_pk_mul_f32 v[128:129], v[128:129], v[128:129]
	v_lshlrev_b32_e32 v134, 2, v88
	v_pk_fma_f32 v[106:107], v[106:107], v[106:107], v[128:129]
	s_waitcnt vmcnt(11)
	v_lshlrev_b32_e32 v128, 16, v124
	s_waitcnt vmcnt(10)
; __device__ __forceinline__ float bflo(unsigned w) { return __uint_as_float(w << 16); }
; __device__ __forceinline__ float bfhi(unsigned w) { return __uint_as_float(w & 0xffff0000u); }
; __device__ __forceinline__ void attn_phase(const Params& p, LAS unsigned char* lds, int l, int mode) {
;     ...
;                 float ss = 0.f;
; #pragma unroll
;                 for (int db = 0; db < 8; ++db) {
;                     f32x4 o = oacc[db] * a0;
;                     o[0] += bflo(x1[db].x) * a1 + bflo(x2[db].x) * a2; o[1] += bfhi(x1[db].x) * a1 + bfhi(x2[db].x) * a2;
;                     o[2] += bflo(x1[db].y) * a1 + bflo(x2[db].y) * a2; o[3] += bfhi(x1[db].y) * a1 + bfhi(x2[db].y) * a2;
;                     oacc[db] = o; ss += (o[0] * o[0] + o[1] * o[1]) + (o[2] * o[2] + o[3] * o[3]);
;                 }
;                 ss += __shfl_xor(ss, 16); ss += __shfl_xor(ss, 32);
	v_and_b32_e32 v129, 0xffff0000, v126
	v_pk_add_f32 v[104:105], v[104:105], v[106:107]
	v_lshlrev_b32_e32 v106, 16, v126
	v_and_b32_e32 v107, 0xffff0000, v124
	v_pk_mul_f32 v[128:129], v[138:139], v[128:129] op_sel:[1,0] op_sel_hi:[0,1]
	v_pk_fma_f32 v[106:107], v[138:139], v[106:107], v[128:129]
	v_lshlrev_b32_e32 v124, 16, v125
	v_pk_fma_f32 v[68:69], v[136:137], v[68:69], v[106:107] op_sel_hi:[0,1,1]
	v_and_b32_e32 v107, 0xffff0000, v125
	v_and_b32_e32 v125, 0xffff0000, v127
	v_lshlrev_b32_e32 v106, 16, v127
	v_pk_mul_f32 v[124:125], v[138:139], v[124:125] op_sel:[1,0] op_sel_hi:[0,1]
	v_pk_fma_f32 v[106:107], v[138:139], v[106:107], v[124:125]
	v_mov_b32_e32 v124, v69
	v_pk_fma_f32 v[70:71], v[136:137], v[70:71], v[106:107] op_sel_hi:[0,1,1]
	v_mov_b32_e32 v125, v71
	v_mov_b32_e32 v106, v68
	v_mov_b32_e32 v107, v70
	v_pk_mul_f32 v[124:125], v[124:125], v[124:125]
	s_waitcnt vmcnt(9)
	v_lshlrev_b32_e32 v126, 16, v98
	s_waitcnt vmcnt(8)
	v_and_b32_e32 v127, 0xffff0000, v122
	v_pk_fma_f32 v[106:107], v[106:107], v[106:107], v[124:125]
	v_lshlrev_b32_e32 v124, 16, v122
	v_and_b32_e32 v125, 0xffff0000, v98
	v_pk_mul_f32 v[126:127], v[138:139], v[126:127] op_sel:[1,0] op_sel_hi:[0,1]
	v_pk_fma_f32 v[124:125], v[138:139], v[124:125], v[126:127]
	v_lshlrev_b32_e32 v98, 16, v99
	v_pk_fma_f32 v[64:65], v[136:137], v[64:65], v[124:125] op_sel_hi:[0,1,1]
	v_and_b32_e32 v125, 0xffff0000, v99
	v_and_b32_e32 v99, 0xffff0000, v123
	v_lshlrev_b32_e32 v124, 16, v123
	v_pk_mul_f32 v[98:99], v[138:139], v[98:99] op_sel:[1,0] op_sel_hi:[0,1]
	s_waitcnt vmcnt(7)
	v_lshlrev_b32_e32 v126, 16, v94
	s_waitcnt vmcnt(6)
	v_and_b32_e32 v127, 0xffff0000, v96
	v_pk_fma_f32 v[98:99], v[138:139], v[124:125], v[98:99]
	v_lshlrev_b32_e32 v124, 16, v96
	v_and_b32_e32 v125, 0xffff0000, v94
	v_pk_mul_f32 v[126:127], v[138:139], v[126:127] op_sel:[1,0] op_sel_hi:[0,1]
	v_pk_fma_f32 v[124:125], v[138:139], v[124:125], v[126:127]
	v_lshlrev_b32_e32 v94, 16, v95
	v_pk_fma_f32 v[60:61], v[136:137], v[60:61], v[124:125] op_sel_hi:[0,1,1]
	v_and_b32_e32 v125, 0xffff0000, v95
	v_and_b32_e32 v95, 0xffff0000, v97
	v_lshlrev_b32_e32 v124, 16, v97
	v_pk_mul_f32 v[94:95], v[138:139], v[94:95] op_sel:[1,0] op_sel_hi:[0,1]
	v_pk_fma_f32 v[66:67], v[136:137], v[66:67], v[98:99] op_sel_hi:[0,1,1]
	v_pk_fma_f32 v[94:95], v[138:139], v[124:125], v[94:95]
	v_mul_f32_e32 v98, v65, v65
	v_mul_f32_e32 v122, v67, v67
	v_pk_fma_f32 v[62:63], v[136:137], v[62:63], v[94:95] op_sel_hi:[0,1,1]
	v_pk_add_f32 v[104:105], v[104:105], v[104:105] op_sel:[0,1] op_sel_hi:[1,0]
	v_pk_add_f32 v[106:107], v[106:107], v[106:107] op_sel:[0,1] op_sel_hi:[1,0]
	v_pk_fma_f32 v[98:99], v[64:65], v[64:65], v[98:99] op_sel_hi:[1,1,0]
	v_pk_fma_f32 v[122:123], v[66:67], v[66:67], v[122:123] op_sel_hi:[1,1,0]
	v_pk_mul_f32 v[94:95], v[60:61], v[60:61]
	v_pk_mul_f32 v[96:97], v[62:63], v[62:63]
	v_mov_b32_e32 v105, v94
	v_mov_b32_e32 v107, v95
	v_mov_b32_e32 v99, v96
	v_mov_b32_e32 v123, v97
	v_pk_add_f32 v[94:95], v[104:105], v[106:107]
	v_pk_add_f32 v[96:97], v[98:99], v[122:123]
	s_waitcnt vmcnt(5)
	v_lshlrev_b32_e32 v98, 16, v90
	s_waitcnt vmcnt(4)
	v_and_b32_e32 v99, 0xffff0000, v92
	v_pk_add_f32 v[94:95], v[94:95], v[96:97]
	v_lshlrev_b32_e32 v96, 16, v92
	v_and_b32_e32 v97, 0xffff0000, v90
	v_pk_mul_f32 v[98:99], v[138:139], v[98:99] op_sel:[1,0] op_sel_hi:[0,1]
	v_pk_fma_f32 v[96:97], v[138:139], v[96:97], v[98:99]
	v_lshlrev_b32_e32 v90, 16, v91
	v_pk_fma_f32 v[56:57], v[136:137], v[56:57], v[96:97] op_sel_hi:[0,1,1]
	v_and_b32_e32 v97, 0xffff0000, v91
	v_and_b32_e32 v91, 0xffff0000, v93
	v_lshlrev_b32_e32 v96, 16, v93
	v_pk_mul_f32 v[90:91], v[138:139], v[90:91] op_sel:[1,0] op_sel_hi:[0,1]
	v_pk_fma_f32 v[90:91], v[138:139], v[96:97], v[90:91]
	v_mov_b32_e32 v92, v57
	v_pk_fma_f32 v[58:59], v[136:137], v[58:59], v[90:91] op_sel_hi:[0,1,1]
	v_mov_b32_e32 v93, v59
	v_mov_b32_e32 v90, v56
	v_mov_b32_e32 v91, v58
	v_pk_mul_f32 v[92:93], v[92:93], v[92:93]
	s_waitcnt vmcnt(3)
	v_lshlrev_b32_e32 v96, 16, v84
	s_waitcnt vmcnt(2)
	v_and_b32_e32 v97, 0xffff0000, v86
	v_pk_fma_f32 v[90:91], v[90:91], v[90:91], v[92:93]
	v_lshlrev_b32_e32 v92, 16, v86
	v_and_b32_e32 v93, 0xffff0000, v84
	v_pk_mul_f32 v[96:97], v[138:139], v[96:97] op_sel:[1,0] op_sel_hi:[0,1]
	v_pk_fma_f32 v[92:93], v[138:139], v[92:93], v[96:97]
	v_lshlrev_b32_e32 v84, 16, v85
	v_pk_fma_f32 v[52:53], v[136:137], v[52:53], v[92:93] op_sel_hi:[0,1,1]
	v_and_b32_e32 v93, 0xffff0000, v85
	v_and_b32_e32 v85, 0xffff0000, v87
	v_lshlrev_b32_e32 v92, 16, v87
	v_pk_mul_f32 v[84:85], v[138:139], v[84:85] op_sel:[1,0] op_sel_hi:[0,1]
	s_waitcnt vmcnt(1)
	v_lshlrev_b32_e32 v96, 16, v80
	s_waitcnt vmcnt(0)
	v_and_b32_e32 v97, 0xffff0000, v82
	v_pk_fma_f32 v[84:85], v[138:139], v[92:93], v[84:85]
	v_lshlrev_b32_e32 v92, 16, v82
	v_and_b32_e32 v93, 0xffff0000, v80
	v_pk_mul_f32 v[96:97], v[138:139], v[96:97] op_sel:[1,0] op_sel_hi:[0,1]
	v_pk_fma_f32 v[92:93], v[138:139], v[92:93], v[96:97]
	v_lshlrev_b32_e32 v80, 16, v81
	v_pk_fma_f32 v[48:49], v[136:137], v[48:49], v[92:93] op_sel_hi:[0,1,1]
	v_and_b32_e32 v93, 0xffff0000, v81
	v_and_b32_e32 v81, 0xffff0000, v83
	v_lshlrev_b32_e32 v92, 16, v83
	v_pk_mul_f32 v[80:81], v[138:139], v[80:81] op_sel:[1,0] op_sel_hi:[0,1]
	v_pk_fma_f32 v[54:55], v[136:137], v[54:55], v[84:85] op_sel_hi:[0,1,1]
	v_pk_fma_f32 v[80:81], v[138:139], v[92:93], v[80:81]
	v_mul_f32_e32 v84, v53, v53
	v_mul_f32_e32 v86, v55, v55
	v_pk_fma_f32 v[50:51], v[136:137], v[50:51], v[80:81] op_sel_hi:[0,1,1]
	v_pk_add_f32 v[94:95], v[94:95], v[94:95] op_sel:[0,1] op_sel_hi:[1,0]
	v_pk_add_f32 v[90:91], v[90:91], v[90:91] op_sel:[0,1] op_sel_hi:[1,0]
	v_pk_fma_f32 v[84:85], v[52:53], v[52:53], v[84:85] op_sel_hi:[1,1,0]
	v_pk_fma_f32 v[86:87], v[54:55], v[54:55], v[86:87] op_sel_hi:[1,1,0]
	v_pk_mul_f32 v[80:81], v[48:49], v[48:49]
	v_pk_mul_f32 v[82:83], v[50:51], v[50:51]
	v_mov_b32_e32 v95, v80
	v_mov_b32_e32 v91, v81
	v_mov_b32_e32 v85, v82
	v_mov_b32_e32 v87, v83
	v_pk_add_f32 v[80:81], v[94:95], v[90:91]
	v_pk_add_f32 v[82:83], v[84:85], v[86:87]
	v_lshlrev_b32_e32 v99, 6, v88
	v_pk_add_f32 v[80:81], v[80:81], v[82:83]
	v_and_b32_e32 v99, 0x3c0, v99
	v_add_f32_e32 v80, v80, v81
	ds_bpermute_b32 v81, v152, v80
	v_and_b32_e32 v134, 32, v134
	s_waitcnt lgkmcnt(0)
; __device__ __forceinline__ unsigned cvt_pk_bf16(float lo, float hi) { unsigned r; asm volatile("v_cvt_pk_bf16_f32 %0, %1, %2" : "=v"(r) : "v"(lo), "v"(hi)); return r; }
; __device__ __forceinline__ void attn_phase(const Params& p, LAS unsigned char* lds, int l, int mode) {
;     ...
;                 ss += __shfl_xor(ss, 16); ss += __shfl_xor(ss, 32);
;                 const float rs = rsqrtf(ss * (1.0f / 128.0f) + 1e-6f);
;                 f32x4 ggv[8];
; #pragma unroll
;                 for (int db = 0; db < 8; ++db) ggv[db] = *(const f32x4*)(gain + h * 128 + 16 * db + 4 * g);
; #pragma unroll
;                 for (int db = 0; db < 8; ++db) {
;                     const f32x4 gg = ggv[db];
;                     const f32x4 o = oacc[db] * rs * gg;
;                     u32x2 w; w.x = cvt_pk_bf16(o[0], o[1]); w.y = cvt_pk_bf16(o[2], o[3]);
;                     *(u32x2*)(mixed + pg8::tiled_off((int)qtok, h * 128 + 16 * db + 4 * g, DM / 64)) = w;
;                 }
;             }
;             asm volatile("s_waitcnt lgkmcnt(0)" ::: "memory"); __builtin_amdgcn_s_barrier(); asm volatile("" ::: "memory");
;             cur = nxt;
	v_add_f32_e32 v80, v80, v81
	ds_bpermute_b32 v81, v200, v80
	s_waitcnt lgkmcnt(0)
	v_add_f32_e32 v80, v80, v81
	v_fmamk_f32 v80, v80, 0x3c000000, v224
	v_cmp_gt_f32_e32 vcc, s42, v80
	v_mul_f32_e32 v81, 0x4b800000, v80
	v_readlane_b32 s42, v252, 53
	v_cndmask_b32_e32 v80, v80, v81, vcc
	v_rsq_f32_e32 v89, v80
	global_load_dwordx4 v[80:83], v[120:121], off
	global_load_dwordx4 v[84:87], v[120:121], off offset:64
	global_load_dwordx4 v[90:93], v[120:121], off offset:128
	global_load_dwordx4 v[94:97], v[120:121], off offset:192
	global_load_dwordx4 v[104:107], v[120:121], off offset:256
	global_load_dwordx4 v[122:125], v[120:121], off offset:320
	global_load_dwordx4 v[126:129], v[120:121], off offset:384
	global_load_dwordx4 v[130:133], v[120:121], off offset:448
	v_readlane_b32 s43, v252, 54
	v_mul_f32_e32 v98, 0x45800000, v89
	v_cndmask_b32_e32 v98, v89, v98, vcc
	v_ashrrev_i32_e32 v89, 2, v88
	v_pk_mul_f32 v[76:77], v[76:77], v[98:99] op_sel_hi:[1,0]
	v_pk_mul_f32 v[78:79], v[78:79], v[98:99] op_sel_hi:[1,0]
	v_and_b32_e32 v89, 0xffffffe0, v89
	v_pk_mul_f32 v[72:73], v[72:73], v[98:99] op_sel_hi:[1,0]
	v_pk_mul_f32 v[74:75], v[74:75], v[98:99] op_sel_hi:[1,0]
	v_pk_mul_f32 v[68:69], v[68:69], v[98:99] op_sel_hi:[1,0]
	v_pk_mul_f32 v[70:71], v[70:71], v[98:99] op_sel_hi:[1,0]
	v_pk_mul_f32 v[64:65], v[64:65], v[98:99] op_sel_hi:[1,0]
	v_pk_mul_f32 v[66:67], v[66:67], v[98:99] op_sel_hi:[1,0]
	v_pk_mul_f32 v[60:61], v[60:61], v[98:99] op_sel_hi:[1,0]
	v_pk_mul_f32 v[62:63], v[62:63], v[98:99] op_sel_hi:[1,0]
	v_pk_mul_f32 v[56:57], v[56:57], v[98:99] op_sel_hi:[1,0]
	v_pk_mul_f32 v[58:59], v[58:59], v[98:99] op_sel_hi:[1,0]
	v_pk_mul_f32 v[52:53], v[52:53], v[98:99] op_sel_hi:[1,0]
	v_pk_mul_f32 v[54:55], v[54:55], v[98:99] op_sel_hi:[1,0]
	v_pk_mul_f32 v[48:49], v[48:49], v[98:99] op_sel_hi:[1,0]
	v_pk_mul_f32 v[50:51], v[50:51], v[98:99] op_sel_hi:[1,0]
	s_mov_b64 vcc, 0
	s_waitcnt vmcnt(7)
	v_pk_mul_f32 v[78:79], v[82:83], v[78:79]
	v_pk_mul_f32 v[76:77], v[80:81], v[76:77]
	v_lshlrev_b32_e32 v80, 7, v88
	v_cvt_pk_bf16_f32 v76, v76, v77
	v_cvt_pk_bf16_f32 v77, v78, v79
	v_or_b32_e32 v78, s46, v89
	v_ashrrev_i32_e32 v79, 31, v78
	v_and_b32_e32 v88, 0x3800, v80
	v_or3_b32 v89, v99, v102, v134
	v_lshlrev_b64 v[80:81], 14, v[78:79]
	v_or_b32_e32 v152, v89, v88
	v_lshl_add_u64 v[80:81], s[42:43], 0, v[80:81]
	v_lshl_add_u64 v[82:83], v[80:81], 0, v[152:153]
	s_waitcnt vmcnt(6)
	v_pk_mul_f32 v[74:75], v[86:87], v[74:75]
	v_pk_mul_f32 v[72:73], v[84:85], v[72:73]
	v_bitop3_b32 v79, v99, v134, v199 bitop3:0x36
	global_store_dwordx2 v[82:83], v[76:77], off
	v_cvt_pk_bf16_f32 v72, v72, v73
	v_cvt_pk_bf16_f32 v73, v74, v75
	v_or_b32_e32 v74, v79, v88
	v_mov_b32_e32 v75, v153
	v_lshl_add_u64 v[76:77], v[80:81], 0, v[74:75]
	global_store_dwordx2 v[76:77], v[72:73], off
	s_waitcnt vmcnt(7)
	v_pk_mul_f32 v[70:71], v[92:93], v[70:71]
	v_pk_mul_f32 v[68:69], v[90:91], v[68:69]
	v_or_b32_e32 v76, 0x400, v88
	v_cvt_pk_bf16_f32 v68, v68, v69
	v_cvt_pk_bf16_f32 v69, v70, v71
	v_or_b32_e32 v70, v89, v76
	v_mov_b32_e32 v71, v153
	v_lshl_add_u64 v[72:73], v[80:81], 0, v[70:71]
	s_waitcnt vmcnt(6)
	v_pk_mul_f32 v[66:67], v[96:97], v[66:67]
	v_pk_mul_f32 v[64:65], v[94:95], v[64:65]
	global_store_dwordx2 v[72:73], v[68:69], off
	v_cvt_pk_bf16_f32 v64, v64, v65
	v_cvt_pk_bf16_f32 v65, v66, v67
	v_or_b32_e32 v66, v79, v76
	v_mov_b32_e32 v67, v153
	v_lshl_add_u64 v[68:69], v[80:81], 0, v[66:67]
	s_waitcnt vmcnt(6)
	v_pk_mul_f32 v[62:63], v[106:107], v[62:63]
	v_pk_mul_f32 v[60:61], v[104:105], v[60:61]
	global_store_dwordx2 v[68:69], v[64:65], off
	v_cvt_pk_bf16_f32 v60, v60, v61
	v_cvt_pk_bf16_f32 v61, v62, v63
	v_or_b32_e32 v62, 1, v78
	v_ashrrev_i32_e32 v63, 31, v62
	v_lshlrev_b64 v[62:63], 14, v[62:63]
	v_lshl_add_u64 v[62:63], s[42:43], 0, v[62:63]
	v_lshl_add_u64 v[64:65], v[62:63], 0, v[152:153]
	s_waitcnt vmcnt(6)
	v_pk_mul_f32 v[58:59], v[124:125], v[58:59]
	v_pk_mul_f32 v[56:57], v[122:123], v[56:57]
	global_store_dwordx2 v[64:65], v[60:61], off
	v_cvt_pk_bf16_f32 v56, v56, v57
	v_cvt_pk_bf16_f32 v57, v58, v59
	v_lshl_add_u64 v[58:59], v[62:63], 0, v[74:75]
	s_waitcnt vmcnt(6)
	v_pk_mul_f32 v[54:55], v[128:129], v[54:55]
	v_pk_mul_f32 v[52:53], v[126:127], v[52:53]
	global_store_dwordx2 v[58:59], v[56:57], off
	v_cvt_pk_bf16_f32 v52, v52, v53
	v_cvt_pk_bf16_f32 v53, v54, v55
	v_lshl_add_u64 v[54:55], v[62:63], 0, v[70:71]
	s_waitcnt vmcnt(6)
	v_pk_mul_f32 v[50:51], v[132:133], v[50:51]
	v_pk_mul_f32 v[48:49], v[130:131], v[48:49]
	global_store_dwordx2 v[54:55], v[52:53], off
	v_cvt_pk_bf16_f32 v48, v48, v49
	v_cvt_pk_bf16_f32 v49, v50, v51
	v_lshl_add_u64 v[50:51], v[62:63], 0, v[66:67]
	global_store_dwordx2 v[50:51], v[48:49], off
	s_waitcnt lgkmcnt(0)
	s_barrier
	v_mov_b64_e32 v[50:51], v[34:35]
	v_mov_b64_e32 v[90:91], v[38:39]
	v_mov_b64_e32 v[94:95], v[42:43]
	v_mov_b64_e32 v[98:99], v[46:47]
	v_mov_b64_e32 v[48:49], v[32:33]
	v_mov_b64_e32 v[88:89], v[36:37]
	v_mov_b64_e32 v[92:93], v[40:41]
	v_mov_b64_e32 v[96:97], v[44:45]
	s_mov_b32 s42, s54
	s_mov_b32 s43, s47
	s_cbranch_scc1 .LBB0_226

; #define LAS __attribute__((address_space(3)))
; __device__ __forceinline__ void attn_phase(const Params& p, LAS unsigned char* lds, int l, int mode) {
;     ...
;             f32x4 sacc[10];
; #pragma unroll
;             for (int i = 0; i < 10; ++i) {
;                 sacc[i] = (f32x4){0.f, 0.f, 0.f, 0.f};
;                 const int kb = kb0 + i, koff = (kb < 8) ? koffP + kb * (16 * 272) : koffC + (kb - 8) * (16 * 272);
; #pragma unroll
;                 for (int s = 0; s < 4; ++s) {
;                     const bf16x8 kf = *(const LAS bf16x8*)(Kl + koff + li * 272 + (32 * s + 8 * g) * 2);
;                     sacc[i] = __builtin_amdgcn_mfma_f32_16x16x32_bf16(kf, qc[s], sacc[i], 0, 0, 0);
;                 }
;             }
.LBB0_311:
	s_xor_b32 s26, s39, 1
	s_lshl_b32 s27, s37, 7
	s_mul_i32 s37, s26, 0x8800
	s_add_i32 s38, s38, 0xffff7800
	v_mov_b32_e32 v119, s38
	v_mov_b32_e32 v179, s37
	v_cndmask_b32_e64 v52, v119, v179, s[4:5]
	v_add_u32_e32 v60, v114, v52
	ds_read_b128 v[52:55], v60
	ds_read_b128 v[56:59], v60 offset:64
	ds_read_b128 v[184:187], v60 offset:128
	ds_read_b128 v[188:191], v60 offset:192
	v_cndmask_b32_e64 v174, v119, v179, s[14:15]
	v_add_u32_e32 v178, s27, v102
	s_sub_i32 s27, 0x7f, s27
	v_cmp_lt_i32_e32 vcc, s27, v129
	s_waitcnt lgkmcnt(3)
	v_mfma_f32_16x16x32_bf16 v[52:55], v[52:55], v[48:51], 0
	s_and_b64 vcc, s[2:3], vcc
	v_readlane_b32 s0, v254, 45
	v_readlane_b32 s1, v254, 46
	s_waitcnt lgkmcnt(2)
	v_mfma_f32_16x16x32_bf16 v[52:55], v[56:59], v[84:87], v[52:55]
	s_mul_i32 s26, s26, 0x9000
	s_add_i32 s13, s13, 0xffff7000
	s_waitcnt lgkmcnt(1)
	v_mfma_f32_16x16x32_bf16 v[52:55], v[184:187], v[88:91], v[52:55]
	s_waitcnt lgkmcnt(0)
	v_mfma_f32_16x16x32_bf16 v[96:99], v[188:191], v[92:95], v[52:55]
	s_nop 4
	v_cndmask_b32_e64 v52, v119, v179, s[42:43]
	v_add_u32_e32 v60, v116, v52
	ds_read_b128 v[52:55], v60
	ds_read_b128 v[56:59], v60 offset:64
	ds_read_b128 v[184:187], v60 offset:128
	ds_read_b128 v[188:191], v60 offset:192
	s_waitcnt lgkmcnt(3)
	v_mfma_f32_16x16x32_bf16 v[52:55], v[52:55], v[48:51], 0
	s_waitcnt lgkmcnt(2)
	v_mfma_f32_16x16x32_bf16 v[52:55], v[56:59], v[84:87], v[52:55]
	s_waitcnt lgkmcnt(1)
	v_mfma_f32_16x16x32_bf16 v[52:55], v[184:187], v[88:91], v[52:55]
	s_waitcnt lgkmcnt(0)
	v_mfma_f32_16x16x32_bf16 v[80:83], v[188:191], v[92:95], v[52:55]
	s_nop 4
	v_cndmask_b32_e64 v52, v119, v179, s[6:7]
	v_add_u32_e32 v60, v115, v52
	ds_read_b128 v[52:55], v60
	ds_read_b128 v[56:59], v60 offset:64
	ds_read_b128 v[184:187], v60 offset:128
	ds_read_b128 v[188:191], v60 offset:192
	s_waitcnt lgkmcnt(3)
	v_mfma_f32_16x16x32_bf16 v[52:55], v[52:55], v[48:51], 0
	s_waitcnt lgkmcnt(2)
	v_mfma_f32_16x16x32_bf16 v[52:55], v[56:59], v[84:87], v[52:55]
	s_waitcnt lgkmcnt(1)
	v_mfma_f32_16x16x32_bf16 v[52:55], v[184:187], v[88:91], v[52:55]
	s_waitcnt lgkmcnt(0)
	v_mfma_f32_16x16x32_bf16 v[76:79], v[188:191], v[92:95], v[52:55]
	s_nop 4
	v_cndmask_b32_e64 v52, v119, v179, s[44:45]
	v_add_u32_e32 v60, v117, v52
	ds_read_b128 v[52:55], v60
	ds_read_b128 v[56:59], v60 offset:64
	ds_read_b128 v[184:187], v60 offset:128
	ds_read_b128 v[188:191], v60 offset:192
	s_waitcnt lgkmcnt(3)
	v_mfma_f32_16x16x32_bf16 v[52:55], v[52:55], v[48:51], 0
	s_waitcnt lgkmcnt(2)
	v_mfma_f32_16x16x32_bf16 v[52:55], v[56:59], v[84:87], v[52:55]
	s_waitcnt lgkmcnt(1)
	v_mfma_f32_16x16x32_bf16 v[52:55], v[184:187], v[88:91], v[52:55]
	s_waitcnt lgkmcnt(0)
	v_mfma_f32_16x16x32_bf16 v[72:75], v[188:191], v[92:95], v[52:55]
	s_nop 4
	v_cndmask_b32_e64 v52, v119, v179, s[10:11]
	v_add_u32_e32 v60, v163, v52
	ds_read_b128 v[52:55], v60
	ds_read_b128 v[56:59], v60 offset:64
	ds_read_b128 v[184:187], v60 offset:128
	ds_read_b128 v[188:191], v60 offset:192
	s_waitcnt lgkmcnt(3)
	v_mfma_f32_16x16x32_bf16 v[52:55], v[52:55], v[48:51], 0
	s_waitcnt lgkmcnt(2)
	v_mfma_f32_16x16x32_bf16 v[52:55], v[56:59], v[84:87], v[52:55]
	s_waitcnt lgkmcnt(1)
	v_mfma_f32_16x16x32_bf16 v[52:55], v[184:187], v[88:91], v[52:55]
	s_waitcnt lgkmcnt(0)
	v_mfma_f32_16x16x32_bf16 v[68:71], v[188:191], v[92:95], v[52:55]
	s_nop 4
	v_cndmask_b32_e64 v52, v119, v179, s[46:47]
	v_add_u32_e32 v60, v164, v52
	ds_read_b128 v[52:55], v60
	ds_read_b128 v[56:59], v60 offset:64
	ds_read_b128 v[184:187], v60 offset:128
	ds_read_b128 v[188:191], v60 offset:192
	s_waitcnt lgkmcnt(3)
	v_mfma_f32_16x16x32_bf16 v[52:55], v[52:55], v[48:51], 0
	s_waitcnt lgkmcnt(2)
	v_mfma_f32_16x16x32_bf16 v[52:55], v[56:59], v[84:87], v[52:55]
	s_waitcnt lgkmcnt(1)
	v_mfma_f32_16x16x32_bf16 v[52:55], v[184:187], v[88:91], v[52:55]
	v_add_u32_e32 v60, v165, v174
	v_add_u32_e32 v174, v166, v174
	s_waitcnt lgkmcnt(0)
	v_mfma_f32_16x16x32_bf16 v[64:67], v[188:191], v[92:95], v[52:55]
	s_nop 2
	ds_read_b128 v[52:55], v60
	ds_read_b128 v[56:59], v60 offset:64
	ds_read_b128 v[184:187], v60 offset:128
	ds_read_b128 v[188:191], v60 offset:192
	s_waitcnt lgkmcnt(3)
	v_mfma_f32_16x16x32_bf16 v[52:55], v[52:55], v[48:51], 0
	s_waitcnt lgkmcnt(2)
	v_mfma_f32_16x16x32_bf16 v[52:55], v[56:59], v[84:87], v[52:55]
	s_waitcnt lgkmcnt(1)
	v_mfma_f32_16x16x32_bf16 v[52:55], v[184:187], v[88:91], v[52:55]
	s_waitcnt lgkmcnt(0)
	v_mfma_f32_16x16x32_bf16 v[60:63], v[188:191], v[92:95], v[52:55]
	s_nop 4
	ds_read_b128 v[52:55], v174
	ds_read_b128 v[56:59], v174 offset:64
	ds_read_b128 v[184:187], v174 offset:128
	ds_read_b128 v[188:191], v174 offset:192
	s_waitcnt lgkmcnt(3)
	v_mfma_f32_16x16x32_bf16 v[52:55], v[52:55], v[48:51], 0
	s_waitcnt lgkmcnt(2)
	v_mfma_f32_16x16x32_bf16 v[52:55], v[56:59], v[84:87], v[52:55]
	s_waitcnt lgkmcnt(1)
	v_mfma_f32_16x16x32_bf16 v[52:55], v[184:187], v[88:91], v[52:55]
	s_waitcnt lgkmcnt(0)
	v_mfma_f32_16x16x32_bf16 v[56:59], v[188:191], v[92:95], v[52:55]
	s_nop 4
	v_cndmask_b32_e64 v52, v119, v179, s[16:17]
	v_add_u32_e32 v180, v167, v52
	ds_read_b128 v[52:55], v180
	ds_read_b128 v[174:177], v180 offset:64
	ds_read_b128 v[184:187], v180 offset:128
	ds_read_b128 v[188:191], v180 offset:192
	s_waitcnt lgkmcnt(3)
	v_mfma_f32_16x16x32_bf16 v[52:55], v[52:55], v[48:51], 0
	v_cndmask_b32_e64 v119, v119, v179, s[48:49]
	v_add_u32_e32 v119, v168, v119
	v_ashrrev_i32_e32 v179, 31, v178
	s_waitcnt lgkmcnt(2)
	v_mfma_f32_16x16x32_bf16 v[52:55], v[174:177], v[84:87], v[52:55]
	s_waitcnt lgkmcnt(1)
	v_mfma_f32_16x16x32_bf16 v[52:55], v[184:187], v[88:91], v[52:55]
	s_waitcnt lgkmcnt(0)
; #define LAS __attribute__((address_space(3)))
; __device__ __forceinline__ void attn_phase(const Params& p, LAS unsigned char* lds, int l, int mode) {
;     ...
;             for (int i = 0; i < 10; ++i) {
;                 sacc[i] = (f32x4){0.f, 0.f, 0.f, 0.f};
;                 const int kb = kb0 + i, koff = (kb < 8) ? koffP + kb * (16 * 272) : koffC + (kb - 8) * (16 * 272);
; #pragma unroll
;                 for (int s = 0; s < 4; ++s) {
;                     const bf16x8 kf = *(const LAS bf16x8*)(Kl + koff + li * 272 + (32 * s + 8 * g) * 2);
;                     sacc[i] = __builtin_amdgcn_mfma_f32_16x16x32_bf16(kf, qc[s], sacc[i], 0, 0, 0);
;                 }
;             }
;             float mx = -1e30f;
; #pragma unroll
;             for (int i = 0; i < 10; ++i)
; #pragma unroll
;                 for (int j = 0; j < 4; ++j) {
;                     const int kj = 16 * (kb0 + i) + 4 * g + j, dist = 128 + qi - kj;
;                     const bool valid = (dist >= 0) && (dist <= 128) && (mbase + kj >= 0);
;                     const float sv = valid ? sacc[i][j] : -1e30f;
;                     sacc[i][j] = sv; mx = fmaxf(mx, sv);
;                 }
;             mx = fmaxf(mx, __shfl_xor(mx, 16)); mx = fmaxf(mx, __shfl_xor(mx, 32));
	v_mfma_f32_16x16x32_bf16 v[52:55], v[188:191], v[92:95], v[52:55]
	ds_read_b128 v[174:177], v119
	s_waitcnt lgkmcnt(0)
	v_mfma_f32_16x16x32_bf16 v[48:51], v[174:177], v[48:51], 0
	ds_read_b128 v[174:177], v119 offset:64
	ds_read_b128 v[184:187], v119 offset:128
	ds_read_b128 v[188:191], v119 offset:192
	s_waitcnt lgkmcnt(2)
	v_mfma_f32_16x16x32_bf16 v[48:51], v[174:177], v[84:87], v[48:51]
	s_waitcnt lgkmcnt(1)
	v_mfma_f32_16x16x32_bf16 v[48:51], v[184:187], v[88:91], v[48:51]
	s_waitcnt lgkmcnt(0)
	v_mfma_f32_16x16x32_bf16 v[48:51], v[188:191], v[92:95], v[48:51]
	v_cndmask_b32_e32 v86, v225, v96, vcc
	v_cmp_le_i32_e32 vcc, s27, v129
	s_and_b64 vcc, s[50:51], vcc
	v_lshlrev_b64 v[84:85], s30, v[178:179]
	v_cndmask_b32_e32 v87, v225, v97, vcc
	v_cmp_lt_i32_e32 vcc, s27, v130
	s_and_b64 vcc, s[54:55], vcc
	s_mov_b32 s30, 0xf149f2ca
	v_cndmask_b32_e32 v88, v225, v98, vcc
	v_cmp_lt_i32_e32 vcc, s27, v131
	s_and_b64 vcc, s[56:57], vcc
	v_max3_f32 v90, v86, s30, v87
	v_cndmask_b32_e32 v89, v225, v99, vcc
	v_cmp_lt_i32_e32 vcc, s27, v132
	s_and_b64 vcc, s[58:59], vcc
	v_max3_f32 v91, v90, v88, v89
	v_cndmask_b32_e32 v80, v225, v80, vcc
	v_cmp_le_i32_e32 vcc, s27, v132
	s_and_b64 vcc, s[60:61], vcc
	v_and_b32_e32 v92, 64, v223
	v_cndmask_b32_e32 v90, v225, v81, vcc
	v_cmp_lt_i32_e32 vcc, s27, v133
	s_and_b64 vcc, s[62:63], vcc
	v_max3_f32 v81, v91, v80, v90
	v_cndmask_b32_e32 v82, v225, v82, vcc
	v_cmp_lt_i32_e32 vcc, s27, v134
	s_and_b64 vcc, s[64:65], vcc
	v_xor_b32_e32 v91, 16, v223
	v_cndmask_b32_e32 v83, v225, v83, vcc
	v_cmp_lt_i32_e32 vcc, s27, v135
	s_and_b64 vcc, s[66:67], vcc
	v_max3_f32 v81, v81, v82, v83
	v_cndmask_b32_e32 v76, v225, v76, vcc
	v_cmp_le_i32_e32 vcc, s27, v135
	s_and_b64 vcc, s[68:69], vcc
	v_add_u32_e32 v92, 64, v92
	v_cndmask_b32_e32 v77, v225, v77, vcc
	v_cmp_lt_i32_e32 vcc, s27, v136
	s_and_b64 vcc, s[70:71], vcc
	v_max3_f32 v81, v81, v76, v77
	v_cndmask_b32_e32 v78, v225, v78, vcc
	v_cmp_lt_i32_e32 vcc, s27, v137
	s_and_b64 vcc, s[72:73], vcc
	s_nop 0
	v_cndmask_b32_e32 v79, v225, v79, vcc
	v_cmp_lt_i32_e32 vcc, s27, v138
	s_and_b64 vcc, s[74:75], vcc
	v_max3_f32 v81, v81, v78, v79
	v_cndmask_b32_e32 v72, v225, v72, vcc
	v_cmp_le_i32_e32 vcc, s27, v138
	s_and_b64 vcc, s[76:77], vcc
	s_nop 0
	v_cndmask_b32_e32 v73, v225, v73, vcc
	v_cmp_lt_i32_e32 vcc, s27, v139
	s_and_b64 vcc, s[78:79], vcc
	v_max3_f32 v81, v81, v72, v73
	v_cndmask_b32_e32 v74, v225, v74, vcc
	v_cmp_lt_i32_e32 vcc, s27, v140
	s_and_b64 vcc, s[80:81], vcc
	s_nop 0
	v_cndmask_b32_e32 v75, v225, v75, vcc
	v_cmp_lt_i32_e32 vcc, s27, v141
	s_and_b64 vcc, s[82:83], vcc
	v_max3_f32 v81, v81, v74, v75
	v_cndmask_b32_e32 v68, v225, v68, vcc
	v_cmp_le_i32_e32 vcc, s27, v141
	s_and_b64 vcc, s[84:85], vcc
	s_nop 0
	v_cndmask_b32_e32 v69, v225, v69, vcc
	v_cmp_lt_i32_e32 vcc, s27, v142
	s_and_b64 vcc, s[88:89], vcc
	v_max3_f32 v81, v81, v68, v69
	v_cndmask_b32_e32 v70, v225, v70, vcc
	v_cmp_lt_i32_e32 vcc, s27, v143
	s_and_b64 vcc, s[90:91], vcc
	s_nop 0
	v_cndmask_b32_e32 v71, v225, v71, vcc
	v_cmp_lt_i32_e32 vcc, s27, v144
	s_and_b64 vcc, s[92:93], vcc
	v_max3_f32 v81, v81, v70, v71
	v_cndmask_b32_e32 v64, v225, v64, vcc
	v_cmp_le_i32_e32 vcc, s27, v144
	s_and_b64 vcc, s[94:95], vcc
	s_nop 0
	v_cndmask_b32_e32 v65, v225, v65, vcc
	v_cmp_lt_i32_e32 vcc, s27, v145
	s_and_b64 vcc, s[96:97], vcc
	v_max3_f32 v81, v81, v64, v65
	v_cndmask_b32_e32 v66, v225, v66, vcc
	v_cmp_lt_i32_e32 vcc, s27, v146
	s_and_b64 vcc, s[98:99], vcc
	s_nop 0
	v_cndmask_b32_e32 v67, v225, v67, vcc
	v_cmp_lt_i32_e32 vcc, s27, v147
	s_and_b64 vcc, s[0:1], vcc
	v_readlane_b32 s0, v254, 47
	v_cndmask_b32_e32 v60, v225, v60, vcc
	v_cmp_le_i32_e32 vcc, s27, v147
	v_readlane_b32 s1, v254, 48
	s_and_b64 vcc, s[0:1], vcc
	v_readlane_b32 s0, v254, 49
	v_cndmask_b32_e32 v61, v225, v61, vcc
	v_cmp_lt_i32_e32 vcc, s27, v148
	v_readlane_b32 s1, v254, 50
	s_and_b64 vcc, s[0:1], vcc
	v_readlane_b32 s0, v254, 51
	v_cndmask_b32_e32 v62, v225, v62, vcc
	v_cmp_lt_i32_e32 vcc, s27, v149
	v_readlane_b32 s1, v254, 52
	s_and_b64 vcc, s[0:1], vcc
	v_readlane_b32 s0, v254, 53
	v_cndmask_b32_e32 v63, v225, v63, vcc
	v_cmp_lt_i32_e32 vcc, s27, v150
	v_readlane_b32 s1, v254, 54
	s_and_b64 vcc, s[0:1], vcc
	v_readlane_b32 s0, v254, 55
	v_cndmask_b32_e32 v56, v225, v56, vcc
	v_cmp_le_i32_e32 vcc, s27, v150
	v_readlane_b32 s1, v254, 56
	s_and_b64 vcc, s[0:1], vcc
	v_readlane_b32 s0, v254, 57
	v_cndmask_b32_e32 v57, v225, v57, vcc
	v_cmp_lt_i32_e32 vcc, s27, v151
	v_readlane_b32 s1, v254, 58
	s_and_b64 vcc, s[0:1], vcc
	v_readlane_b32 s0, v254, 59
	v_cndmask_b32_e32 v58, v225, v58, vcc
	v_cmp_lt_i32_e32 vcc, s27, v156
	v_readlane_b32 s1, v254, 60
	s_and_b64 vcc, s[0:1], vcc
	v_readlane_b32 s0, v254, 41
	v_cndmask_b32_e32 v59, v225, v59, vcc
	v_cmp_lt_i32_e32 vcc, s27, v157
	v_readlane_b32 s1, v254, 42
	s_and_b64 vcc, s[0:1], vcc
	v_readlane_b32 s0, v254, 36
	v_cndmask_b32_e32 v52, v225, v52, vcc
	v_cmp_le_i32_e32 vcc, s27, v157
	v_readlane_b32 s1, v254, 37
	s_and_b64 vcc, s[0:1], vcc
	v_readlane_b32 s0, v254, 43
	v_cndmask_b32_e32 v53, v225, v53, vcc
	v_cmp_lt_i32_e32 vcc, s27, v158
	v_readlane_b32 s1, v254, 44
	s_and_b64 vcc, s[0:1], vcc
	v_readlane_b32 s0, v254, 39
	v_cndmask_b32_e32 v54, v225, v54, vcc
	v_cmp_lt_i32_e32 vcc, s27, v159
	v_readlane_b32 s1, v254, 40
	s_and_b64 vcc, s[0:1], vcc
	v_readlane_b32 s0, v254, 61
	v_cndmask_b32_e32 v55, v225, v55, vcc
	v_cmp_lt_i32_e32 vcc, s27, v160
	v_readlane_b32 s1, v254, 62
	s_and_b64 vcc, s[0:1], vcc
	v_readlane_b32 s0, v254, 63
	v_max3_f32 v81, v81, v66, v67
	v_cndmask_b32_e32 v48, v225, v48, vcc
	v_cmp_le_i32_e32 vcc, s27, v160
	v_readlane_b32 s1, v255, 0
	v_max3_f32 v81, v81, v60, v61
	s_and_b64 vcc, s[0:1], vcc
	v_readlane_b32 s0, v255, 1
	v_max3_f32 v81, v81, v62, v63
	v_cndmask_b32_e32 v49, v225, v49, vcc
	v_cmp_lt_i32_e32 vcc, s27, v161
	v_readlane_b32 s1, v255, 2
	v_max3_f32 v81, v81, v56, v57
	s_and_b64 vcc, s[0:1], vcc
	v_readlane_b32 s0, v255, 3
	v_max3_f32 v81, v81, v58, v59
	v_cndmask_b32_e32 v50, v225, v50, vcc
	v_cmp_lt_i32_e32 vcc, s27, v162
	v_readlane_b32 s1, v255, 4
	v_max3_f32 v81, v81, v52, v53
	s_and_b64 vcc, s[0:1], vcc
	v_max3_f32 v81, v81, v54, v55
	v_cndmask_b32_e32 v51, v225, v51, vcc
	v_cmp_lt_i32_e32 vcc, v91, v92
	v_max3_f32 v81, v81, v48, v49
	v_max3_f32 v81, v81, v50, v51
	v_cndmask_b32_e32 v91, v223, v91, vcc
	v_lshlrev_b32_e32 v91, 2, v91
	ds_bpermute_b32 v93, v91, v81
	s_waitcnt lgkmcnt(0)
; #define LAS __attribute__((address_space(3)))
; __device__ __forceinline__ void attn_phase(const Params& p, LAS unsigned char* lds, int l, int mode) {
;     ...
;             mx = fmaxf(mx, __shfl_xor(mx, 16)); mx = fmaxf(mx, __shfl_xor(mx, 32));
;             float lsum = 0.f;
; #pragma unroll
;             for (int i = 0; i < 10; ++i)
; #pragma unroll
;                 for (int j = 0; j < 4; ++j) { const float pv = __builtin_amdgcn_exp2f(sacc[i][j] - mx); sacc[i][j] = pv; lsum += pv; }
;             lsum += __shfl_xor(lsum, 16); lsum += __shfl_xor(lsum, 32);
;             u32x2 x1[8], x2[8]; float l1 = 0.f, l2 = 0.f;
;             if (mode) {
;                 l1 = lse[qtok * 8 + h]; l2 = lse[((size_t)T_TOK + qtok) * 8 + h];
;                 const bf16_t* p1 = opart + qtok * 1024 + h * 128 + 4 * g; const bf16_t* p2 = p1 + (size_t)T_TOK * 1024;
; #pragma unroll
;                 for (int db = 0; db < 8; ++db) { x1[db] = *(const u32x2*)(p1 + 16 * db); x2[db] = *(const u32x2*)(p2 + 16 * db); }
;             }
;             f32x4 oacc[8];
; #pragma unroll
;             for (int db = 0; db < 8; ++db) oacc[db] = (f32x4){0.f, 0.f, 0.f, 0.f};
;             const int vlane = (4 * g + (li >> 2)) * 288 + (4 * (li & 3)) * 2;
; #pragma unroll
;             for (int t = 0; t < 5; ++t) {
;                 u32x4 pw; pw.x = cvt_pk_bf16(sacc[2 * t][0], sacc[2 * t][1]); pw.y = cvt_pk_bf16(sacc[2 * t][2], sacc[2 * t][3]);
;                 pw.z = cvt_pk_bf16(sacc[2 * t + 1][0], sacc[2 * t + 1][1]); pw.w = cvt_pk_bf16(sacc[2 * t + 1][2], sacc[2 * t + 1][3]);
;                 const bf16x8 pf = __builtin_bit_cast(bf16x8, pw);
;                 const int kbv = kb0 + 2 * t, voff = (kbv < 8) ? voffP + kbv * (16 * 288) : voffC + (kbv - 8) * (16 * 288);
;                 const LAS unsigned char* vb = Vl + voff + vlane;
; #pragma unroll
;                 for (int db = 0; db < 8; ++db) {
;                     const s16x4 lo = __builtin_bit_cast(s16x4, __builtin_amdgcn_ds_read_tr16_b64_v4i16((LAS s16x4*)(vb + db * 32)));
;                     const s16x4 hi = __builtin_bit_cast(s16x4, __builtin_amdgcn_ds_read_tr16_b64_v4i16((LAS s16x4*)(vb + 16 * 288 + db * 32)));
;                     const bf16x8 vf = __builtin_shufflevector(lo, hi, 0, 1, 2, 3, 4, 5, 6, 7);
;                     oacc[db] = __builtin_amdgcn_mfma_f32_16x16x32_bf16(vf, pf, oacc[db], 0, 0, 0);
	v_max_f32_e32 v93, v93, v93
	v_max_f32_e32 v81, v81, v93
	v_xor_b32_e32 v93, 32, v223
	v_cmp_lt_i32_e32 vcc, v93, v92
	s_nop 1
	v_cndmask_b32_e32 v92, v223, v93, vcc
	v_lshlrev_b32_e32 v92, 2, v92
	ds_bpermute_b32 v93, v92, v81
	s_waitcnt lgkmcnt(0)
	v_max_f32_e32 v93, v93, v93
	v_max_f32_e32 v81, v81, v93
	v_sub_f32_e32 v86, v86, v81
	v_exp_f32_e32 v93, v86
	v_sub_f32_e32 v87, v87, v81
	v_exp_f32_e32 v94, v87
	v_sub_f32_e32 v87, v88, v81
	v_exp_f32_e32 v88, v87
	v_sub_f32_e32 v87, v89, v81
	v_exp_f32_e32 v89, v87
	v_sub_f32_e32 v80, v80, v81
	v_add_f32_e32 v86, 0, v93
	v_exp_f32_e32 v95, v80
	v_add_f32_e32 v86, v94, v86
	v_add_f32_e32 v86, v88, v86
	v_add_f32_e32 v86, v89, v86
	v_add_f32_e32 v80, v95, v86
	v_sub_f32_e32 v86, v90, v81
	v_exp_f32_e32 v90, v86
	v_sub_f32_e32 v82, v82, v81
	v_exp_f32_e32 v96, v82
	v_sub_f32_e32 v82, v83, v81
	v_exp_f32_e32 v97, v82
	v_sub_f32_e32 v76, v76, v81
	v_exp_f32_e32 v76, v76
	v_sub_f32_e32 v77, v77, v81
	v_add_f32_e32 v80, v90, v80
	v_exp_f32_e32 v77, v77
	v_sub_f32_e32 v78, v78, v81
	v_add_f32_e32 v80, v96, v80
	v_exp_f32_e32 v78, v78
	v_sub_f32_e32 v79, v79, v81
	v_add_f32_e32 v80, v97, v80
	v_exp_f32_e32 v79, v79
	v_add_f32_e32 v80, v76, v80
	v_add_f32_e32 v80, v77, v80
	v_add_f32_e32 v80, v78, v80
	v_sub_f32_e32 v72, v72, v81
	v_add_f32_e32 v82, v79, v80
	v_exp_f32_e32 v80, v72
	v_sub_f32_e32 v73, v73, v81
	v_sub_f32_e32 v68, v68, v81
	v_exp_f32_e32 v68, v68
	v_add_f32_e32 v72, v80, v82
	v_exp_f32_e32 v82, v73
	v_sub_f32_e32 v73, v74, v81
	v_exp_f32_e32 v83, v73
	v_sub_f32_e32 v73, v75, v81
	v_exp_f32_e32 v87, v73
	v_sub_f32_e32 v69, v69, v81
	v_add_f32_e32 v72, v82, v72
	v_exp_f32_e32 v69, v69
	v_sub_f32_e32 v70, v70, v81
	v_add_f32_e32 v72, v83, v72
	v_exp_f32_e32 v70, v70
	v_sub_f32_e32 v71, v71, v81
	v_add_f32_e32 v72, v87, v72
	v_exp_f32_e32 v71, v71
	v_add_f32_e32 v72, v68, v72
	v_add_f32_e32 v72, v69, v72
	v_add_f32_e32 v72, v70, v72
	v_sub_f32_e32 v64, v64, v81
	v_add_f32_e32 v73, v71, v72
	v_exp_f32_e32 v72, v64
	v_sub_f32_e32 v65, v65, v81
	v_sub_f32_e32 v60, v60, v81
	v_exp_f32_e32 v60, v60
	v_add_f32_e32 v64, v72, v73
	v_exp_f32_e32 v73, v65
	v_sub_f32_e32 v65, v66, v81
	v_exp_f32_e32 v74, v65
	v_sub_f32_e32 v65, v67, v81
	v_exp_f32_e32 v75, v65
	v_sub_f32_e32 v61, v61, v81
	v_add_f32_e32 v64, v73, v64
	v_exp_f32_e32 v61, v61
	v_sub_f32_e32 v62, v62, v81
	v_add_f32_e32 v64, v74, v64
	v_exp_f32_e32 v62, v62
	v_sub_f32_e32 v63, v63, v81
	v_add_f32_e32 v64, v75, v64
	v_exp_f32_e32 v63, v63
	v_add_f32_e32 v64, v60, v64
	v_add_f32_e32 v64, v61, v64
	v_add_f32_e32 v64, v62, v64
	v_sub_f32_e32 v56, v56, v81
	v_add_f32_e32 v65, v63, v64
	v_exp_f32_e32 v64, v56
	v_sub_f32_e32 v57, v57, v81
	v_sub_f32_e32 v52, v52, v81
	v_exp_f32_e32 v52, v52
	v_add_f32_e32 v56, v64, v65
	v_exp_f32_e32 v65, v57
	v_sub_f32_e32 v57, v58, v81
	v_exp_f32_e32 v66, v57
	v_sub_f32_e32 v57, v59, v81
	v_exp_f32_e32 v67, v57
	v_sub_f32_e32 v53, v53, v81
	v_add_f32_e32 v56, v65, v56
	v_exp_f32_e32 v53, v53
	v_sub_f32_e32 v54, v54, v81
	v_add_f32_e32 v56, v66, v56
	v_exp_f32_e32 v54, v54
	v_sub_f32_e32 v55, v55, v81
	v_add_f32_e32 v56, v67, v56
	v_exp_f32_e32 v55, v55
	v_add_f32_e32 v56, v52, v56
	v_add_f32_e32 v56, v53, v56
	v_add_f32_e32 v56, v54, v56
	v_sub_f32_e32 v48, v48, v81
	v_add_f32_e32 v57, v55, v56
	v_exp_f32_e32 v56, v48
	v_sub_f32_e32 v49, v49, v81
	v_add_f32_e32 v48, v56, v57
	v_exp_f32_e32 v57, v49
	v_sub_f32_e32 v49, v50, v81
	v_exp_f32_e32 v58, v49
	v_sub_f32_e32 v49, v51, v81
	v_exp_f32_e32 v59, v49
	v_add_f32_e32 v48, v57, v48
	v_add_f32_e32 v48, v58, v48
	v_add_f32_e32 v48, v59, v48
	ds_bpermute_b32 v49, v91, v48
	s_waitcnt lgkmcnt(0)
	v_add_f32_e32 v48, v48, v49
	ds_bpermute_b32 v49, v92, v48
	s_waitcnt lgkmcnt(0)
	v_add_f32_e32 v86, v48, v49
	v_cvt_pk_bf16_f32 v48, v93, v94
	v_cvt_pk_bf16_f32 v49, v88, v89
	v_mov_b32_e32 v88, s13
	v_mov_b32_e32 v89, s26
	v_cvt_pk_bf16_f32 v50, v95, v90
	v_cndmask_b32_e64 v90, v88, v89, s[4:5]
	v_add_u32_e32 v98, v169, v90
	v_cvt_pk_bf16_f32 v51, v96, v97
	ds_read_b64_tr_b16 v[92:93], v98 offset:4608
	ds_read_b64_tr_b16 v[90:91], v98
	ds_read_b64_tr_b16 v[94:95], v98 offset:32
	ds_read_b64_tr_b16 v[96:97], v98 offset:4640
	ds_read_b64_tr_b16 v[174:175], v98 offset:64
	ds_read_b64_tr_b16 v[176:177], v98 offset:4672
	ds_read_b64_tr_b16 v[178:179], v98 offset:96
	ds_read_b64_tr_b16 v[180:181], v98 offset:4704
	ds_read_b64_tr_b16 v[182:183], v98 offset:128
	ds_read_b64_tr_b16 v[184:185], v98 offset:4736
	ds_read_b64_tr_b16 v[186:187], v98 offset:160
	ds_read_b64_tr_b16 v[188:189], v98 offset:4768
	ds_read_b64_tr_b16 v[190:191], v98 offset:192
	ds_read_b64_tr_b16 v[192:193], v98 offset:4800
	ds_read_b64_tr_b16 v[194:195], v98 offset:224
	ds_read_b64_tr_b16 v[196:197], v98 offset:4832
	v_cvt_pk_bf16_f32 v76, v76, v77
	v_cvt_pk_bf16_f32 v77, v78, v79
	v_cvt_pk_bf16_f32 v78, v80, v82
	v_cndmask_b32_e64 v80, v88, v89, s[6:7]
	v_add_u32_e32 v80, v170, v80
	s_waitcnt lgkmcnt(14)
	v_mfma_f32_16x16x32_bf16 v[90:93], v[90:93], v[48:51], 0
	v_cvt_pk_bf16_f32 v79, v83, v87
	s_add_u32 s13, s18, s35
	s_addc_u32 s18, s19, 0
	s_waitcnt lgkmcnt(12)
	v_mfma_f32_16x16x32_bf16 v[94:97], v[94:97], v[48:51], 0
	s_add_u32 s13, s13, s20
	s_addc_u32 s19, s18, s21
	s_add_u32 s18, s13, 0xffffc000
	s_waitcnt lgkmcnt(10)
	v_mfma_f32_16x16x32_bf16 v[174:177], v[174:177], v[48:51], 0
	s_addc_u32 s19, s19, -1
	s_lshl_b32 s52, s12, 8
	s_waitcnt lgkmcnt(8)
	v_mfma_f32_16x16x32_bf16 v[178:181], v[178:181], v[48:51], 0
	s_waitcnt lgkmcnt(6)
	v_mfma_f32_16x16x32_bf16 v[182:185], v[182:185], v[48:51], 0
	s_waitcnt lgkmcnt(4)
	v_mfma_f32_16x16x32_bf16 v[186:189], v[186:189], v[48:51], 0
	s_waitcnt lgkmcnt(2)
; #define LAS __attribute__((address_space(3)))
; __device__ __forceinline__ unsigned cvt_pk_bf16(float lo, float hi) { unsigned r; asm volatile("v_cvt_pk_bf16_f32 %0, %1, %2" : "=v"(r) : "v"(lo), "v"(hi)); return r; }
; __device__ __forceinline__ void attn_phase(const Params& p, LAS unsigned char* lds, int l, int mode) {
;     ...
; #pragma unroll
;             for (int t = 0; t < 5; ++t) {
;                 u32x4 pw; pw.x = cvt_pk_bf16(sacc[2 * t][0], sacc[2 * t][1]); pw.y = cvt_pk_bf16(sacc[2 * t][2], sacc[2 * t][3]);
;                 pw.z = cvt_pk_bf16(sacc[2 * t + 1][0], sacc[2 * t + 1][1]); pw.w = cvt_pk_bf16(sacc[2 * t + 1][2], sacc[2 * t + 1][3]);
;                 const bf16x8 pf = __builtin_bit_cast(bf16x8, pw);
;                 const int kbv = kb0 + 2 * t, voff = (kbv < 8) ? voffP + kbv * (16 * 288) : voffC + (kbv - 8) * (16 * 288);
;                 const LAS unsigned char* vb = Vl + voff + vlane;
; #pragma unroll
;                 for (int db = 0; db < 8; ++db) {
;                     const s16x4 lo = __builtin_bit_cast(s16x4, __builtin_amdgcn_ds_read_tr16_b64_v4i16((LAS s16x4*)(vb + db * 32)));
;                     const s16x4 hi = __builtin_bit_cast(s16x4, __builtin_amdgcn_ds_read_tr16_b64_v4i16((LAS s16x4*)(vb + 16 * 288 + db * 32)));
;                     const bf16x8 vf = __builtin_shufflevector(lo, hi, 0, 1, 2, 3, 4, 5, 6, 7);
;                     oacc[db] = __builtin_amdgcn_mfma_f32_16x16x32_bf16(vf, pf, oacc[db], 0, 0, 0);
;                 }
;             }
	v_mfma_f32_16x16x32_bf16 v[190:193], v[190:193], v[48:51], 0
	s_waitcnt lgkmcnt(0)
	v_mfma_f32_16x16x32_bf16 v[48:51], v[194:197], v[48:51], 0
	ds_read_b64_tr_b16 v[196:197], v80 offset:4608
	ds_read_b64_tr_b16 v[194:195], v80
	ds_read_b64_tr_b16 v[198:199], v80 offset:32
	ds_read_b64_tr_b16 v[200:201], v80 offset:4640
	s_waitcnt lgkmcnt(2)
	v_mfma_f32_16x16x32_bf16 v[90:93], v[194:197], v[76:79], v[90:93]
	ds_read_b64_tr_b16 v[194:195], v80 offset:64
	ds_read_b64_tr_b16 v[196:197], v80 offset:4672
	s_waitcnt lgkmcnt(0)
	v_mfma_f32_16x16x32_bf16 v[174:177], v[194:197], v[76:79], v[174:177]
	ds_read_b64_tr_b16 v[194:195], v80 offset:96
	ds_read_b64_tr_b16 v[196:197], v80 offset:4704
	s_waitcnt lgkmcnt(0)
	v_mfma_f32_16x16x32_bf16 v[178:181], v[194:197], v[76:79], v[178:181]
	ds_read_b64_tr_b16 v[194:195], v80 offset:128
	ds_read_b64_tr_b16 v[196:197], v80 offset:4736
	s_waitcnt lgkmcnt(0)
	v_mfma_f32_16x16x32_bf16 v[182:185], v[194:197], v[76:79], v[182:185]
	ds_read_b64_tr_b16 v[194:195], v80 offset:160
	ds_read_b64_tr_b16 v[196:197], v80 offset:4768
	s_waitcnt lgkmcnt(0)
	v_mfma_f32_16x16x32_bf16 v[186:189], v[194:197], v[76:79], v[186:189]
	ds_read_b64_tr_b16 v[194:195], v80 offset:192
	ds_read_b64_tr_b16 v[196:197], v80 offset:4800
	s_waitcnt lgkmcnt(0)
	v_mfma_f32_16x16x32_bf16 v[190:193], v[194:197], v[76:79], v[190:193]
	ds_read_b64_tr_b16 v[194:195], v80 offset:224
	ds_read_b64_tr_b16 v[196:197], v80 offset:4832
	v_cvt_pk_bf16_f32 v68, v68, v69
	v_cvt_pk_bf16_f32 v69, v70, v71
	v_cvt_pk_bf16_f32 v70, v72, v73
	v_cndmask_b32_e64 v72, v88, v89, s[10:11]
	v_add_u32_e32 v80, v171, v72
	v_mfma_f32_16x16x32_bf16 v[94:97], v[198:201], v[76:79], v[94:97]
	v_cvt_pk_bf16_f32 v71, v74, v75
	s_waitcnt lgkmcnt(0)
	v_mfma_f32_16x16x32_bf16 v[48:51], v[194:197], v[76:79], v[48:51]
	ds_read_b64_tr_b16 v[74:75], v80 offset:4608
	ds_read_b64_tr_b16 v[72:73], v80
	ds_read_b64_tr_b16 v[76:77], v80 offset:32
	ds_read_b64_tr_b16 v[78:79], v80 offset:4640
	s_waitcnt lgkmcnt(2)
	v_mfma_f32_16x16x32_bf16 v[72:75], v[72:75], v[68:71], v[90:93]
	s_nop 2
	ds_read_b64_tr_b16 v[90:91], v80 offset:64
	ds_read_b64_tr_b16 v[92:93], v80 offset:4672
	s_waitcnt lgkmcnt(2)
	v_mfma_f32_16x16x32_bf16 v[76:79], v[76:79], v[68:71], v[94:97]
	s_nop 2
	ds_read_b64_tr_b16 v[94:95], v80 offset:96
	ds_read_b64_tr_b16 v[96:97], v80 offset:4704
	s_waitcnt lgkmcnt(2)
	v_mfma_f32_16x16x32_bf16 v[90:93], v[90:93], v[68:71], v[174:177]
	s_nop 2
	ds_read_b64_tr_b16 v[174:175], v80 offset:128
	ds_read_b64_tr_b16 v[176:177], v80 offset:4736
	s_waitcnt lgkmcnt(2)
	v_mfma_f32_16x16x32_bf16 v[94:97], v[94:97], v[68:71], v[178:181]
	s_nop 2
	ds_read_b64_tr_b16 v[178:179], v80 offset:160
	ds_read_b64_tr_b16 v[180:181], v80 offset:4768
	s_waitcnt lgkmcnt(2)
	v_mfma_f32_16x16x32_bf16 v[174:177], v[174:177], v[68:71], v[182:185]
	s_nop 2
	ds_read_b64_tr_b16 v[182:183], v80 offset:192
	ds_read_b64_tr_b16 v[184:185], v80 offset:4800
	s_waitcnt lgkmcnt(2)
	v_mfma_f32_16x16x32_bf16 v[178:181], v[178:181], v[68:71], v[186:189]
	s_nop 2
	ds_read_b64_tr_b16 v[186:187], v80 offset:224
	ds_read_b64_tr_b16 v[188:189], v80 offset:4832
	v_cvt_pk_bf16_f32 v60, v60, v61
	v_cvt_pk_bf16_f32 v61, v62, v63
	v_cvt_pk_bf16_f32 v62, v64, v65
	v_cndmask_b32_e64 v64, v88, v89, s[14:15]
	v_add_u32_e32 v80, v172, v64
	s_waitcnt lgkmcnt(2)
	v_mfma_f32_16x16x32_bf16 v[182:185], v[182:185], v[68:71], v[190:193]
	v_cvt_pk_bf16_f32 v63, v66, v67
	s_waitcnt lgkmcnt(0)
	v_mfma_f32_16x16x32_bf16 v[48:51], v[186:189], v[68:71], v[48:51]
	ds_read_b64_tr_b16 v[66:67], v80 offset:4608
	ds_read_b64_tr_b16 v[64:65], v80
	ds_read_b64_tr_b16 v[68:69], v80 offset:32
	ds_read_b64_tr_b16 v[70:71], v80 offset:4640
	s_waitcnt lgkmcnt(2)
	v_mfma_f32_16x16x32_bf16 v[64:67], v[64:67], v[60:63], v[72:75]
	s_nop 2
	ds_read_b64_tr_b16 v[72:73], v80 offset:64
	ds_read_b64_tr_b16 v[74:75], v80 offset:4672
	s_waitcnt lgkmcnt(0)
	v_mfma_f32_16x16x32_bf16 v[90:93], v[72:75], v[60:63], v[90:93]
	ds_read_b64_tr_b16 v[72:73], v80 offset:96
	ds_read_b64_tr_b16 v[74:75], v80 offset:4704
	s_waitcnt lgkmcnt(0)
	v_mfma_f32_16x16x32_bf16 v[94:97], v[72:75], v[60:63], v[94:97]
	ds_read_b64_tr_b16 v[72:73], v80 offset:128
	ds_read_b64_tr_b16 v[74:75], v80 offset:4736
	s_waitcnt lgkmcnt(0)
	v_mfma_f32_16x16x32_bf16 v[174:177], v[72:75], v[60:63], v[174:177]
	ds_read_b64_tr_b16 v[72:73], v80 offset:160
	ds_read_b64_tr_b16 v[74:75], v80 offset:4768
	s_waitcnt lgkmcnt(0)
	v_mfma_f32_16x16x32_bf16 v[178:181], v[72:75], v[60:63], v[178:181]
	ds_read_b64_tr_b16 v[72:73], v80 offset:192
	ds_read_b64_tr_b16 v[74:75], v80 offset:4800
	s_waitcnt lgkmcnt(0)
; #define LAS __attribute__((address_space(3)))
; __device__ __forceinline__ unsigned cvt_pk_bf16(float lo, float hi) { unsigned r; asm volatile("v_cvt_pk_bf16_f32 %0, %1, %2" : "=v"(r) : "v"(lo), "v"(hi)); return r; }
; __device__ __forceinline__ void attn_phase(const Params& p, LAS unsigned char* lds, int l, int mode) {
;     ...
;                     const s16x4 hi = __builtin_bit_cast(s16x4, __builtin_amdgcn_ds_read_tr16_b64_v4i16((LAS s16x4*)(vb + 16 * 288 + db * 32)));
;                     const bf16x8 vf = __builtin_shufflevector(lo, hi, 0, 1, 2, 3, 4, 5, 6, 7);
;                     oacc[db] = __builtin_amdgcn_mfma_f32_16x16x32_bf16(vf, pf, oacc[db], 0, 0, 0);
;                 }
;             }
;             const float inv = 1.0f / lsum, lse0 = mx + __builtin_amdgcn_logf(lsum);
;             if (mode == 0) {
;                 bf16_t* op = opart + ((size_t)(cur.br - 1) * T_TOK + qtok) * 1024 + h * 128 + 4 * g;
; #pragma unroll
;                 for (int db = 0; db < 8; ++db) { const f32x4 o = oacc[db] * inv; u32x2 w; w.x = cvt_pk_bf16(o[0], o[1]); w.y = cvt_pk_bf16(o[2], o[3]); *(u32x2*)(op + 16 * db) = w; }
;                 if (g == 0) lse[((size_t)(cur.br - 1) * T_TOK + qtok) * 8 + h] = lse0;
	v_mfma_f32_16x16x32_bf16 v[182:185], v[72:75], v[60:63], v[182:185]
	ds_read_b64_tr_b16 v[72:73], v80 offset:224
	ds_read_b64_tr_b16 v[74:75], v80 offset:4832
	v_cvt_pk_bf16_f32 v186, v52, v53
	v_cndmask_b32_e64 v52, v88, v89, s[16:17]
	v_add_u32_e32 v80, v173, v52
	v_cvt_pk_bf16_f32 v187, v54, v55
	v_cvt_pk_bf16_f32 v188, v56, v57
	v_cvt_pk_bf16_f32 v189, v58, v59
	ds_read_b64_tr_b16 v[54:55], v80 offset:4608
	ds_read_b64_tr_b16 v[52:53], v80
	ds_read_b64_tr_b16 v[56:57], v80 offset:32
	ds_read_b64_tr_b16 v[58:59], v80 offset:4640
	v_mfma_f32_16x16x32_bf16 v[68:71], v[68:71], v[60:63], v[76:79]
	s_waitcnt lgkmcnt(2)
	v_mfma_f32_16x16x32_bf16 v[76:79], v[52:55], v[186:189], v[64:67]
	ds_read_b64_tr_b16 v[52:53], v80 offset:64
	ds_read_b64_tr_b16 v[54:55], v80 offset:4672
	v_mfma_f32_16x16x32_bf16 v[48:51], v[72:75], v[60:63], v[48:51]
	s_waitcnt lgkmcnt(2)
	v_mfma_f32_16x16x32_bf16 v[72:75], v[56:59], v[186:189], v[68:71]
	s_waitcnt lgkmcnt(0)
	v_mfma_f32_16x16x32_bf16 v[68:71], v[52:55], v[186:189], v[90:93]
	ds_read_b64_tr_b16 v[52:53], v80 offset:96
	ds_read_b64_tr_b16 v[54:55], v80 offset:4704
	s_waitcnt lgkmcnt(0)
	v_mfma_f32_16x16x32_bf16 v[64:67], v[52:55], v[186:189], v[94:97]
	ds_read_b64_tr_b16 v[52:53], v80 offset:128
	ds_read_b64_tr_b16 v[54:55], v80 offset:4736
	s_waitcnt lgkmcnt(0)
	v_mfma_f32_16x16x32_bf16 v[60:63], v[52:55], v[186:189], v[174:177]
	ds_read_b64_tr_b16 v[52:53], v80 offset:160
	ds_read_b64_tr_b16 v[54:55], v80 offset:4768
	s_waitcnt lgkmcnt(0)
	v_mfma_f32_16x16x32_bf16 v[56:59], v[52:55], v[186:189], v[178:181]
	ds_read_b64_tr_b16 v[52:53], v80 offset:192
	ds_read_b64_tr_b16 v[54:55], v80 offset:4800
	ds_read_b64_tr_b16 v[88:89], v80 offset:224
	ds_read_b64_tr_b16 v[90:91], v80 offset:4832
	v_div_scale_f32 v80, s[26:27], v86, v86, 1.0
	v_rcp_f32_e32 v82, v80
	s_waitcnt lgkmcnt(0)
	v_mfma_f32_16x16x32_bf16 v[48:51], v[88:91], v[186:189], v[48:51]
	v_fma_f32 v83, -v80, v82, 1.0
	v_fmac_f32_e32 v82, v83, v82
	v_div_scale_f32 v83, vcc, 1.0, v86, 1.0
	v_mul_f32_e32 v87, v83, v82
	v_fma_f32 v88, -v80, v87, v83
	v_fmac_f32_e32 v87, v88, v82
	v_fma_f32 v80, -v80, v87, v83
	v_mfma_f32_16x16x32_bf16 v[52:55], v[52:55], v[186:189], v[182:185]
	v_div_fmas_f32 v80, v80, v82, v87
	v_lshl_add_u64 v[82:83], s[18:19], 0, v[84:85]
	v_readlane_b32 s18, v252, 61
	v_lshlrev_b64 v[84:85], 11, v[82:83]
	v_readlane_b32 s19, v252, 62
	v_div_fixup_f32 v80, v80, v86, 1.0
	v_pk_mul_f32 v[76:77], v[80:81], v[76:77] op_sel_hi:[0,1]
	v_lshl_add_u64 v[84:85], s[18:19], 0, v[84:85]
	v_lshl_add_u64 v[84:85], v[84:85], 0, s[52:53]
	v_lshl_add_u64 v[84:85], v[84:85], 0, v[152:153]
	v_pk_mul_f32 v[72:73], v[80:81], v[72:73] op_sel_hi:[0,1]
	v_pk_mul_f32 v[68:69], v[80:81], v[68:69] op_sel_hi:[0,1]
	v_pk_mul_f32 v[64:65], v[80:81], v[64:65] op_sel_hi:[0,1]
	v_pk_mul_f32 v[60:61], v[80:81], v[60:61] op_sel_hi:[0,1]
	v_pk_mul_f32 v[56:57], v[80:81], v[56:57] op_sel_hi:[0,1]
	v_pk_mul_f32 v[52:53], v[80:81], v[52:53] op_sel_hi:[0,1]
	v_pk_mul_f32 v[48:49], v[80:81], v[48:49] op_sel_hi:[0,1]
	v_pk_mul_f32 v[78:79], v[80:81], v[78:79] op_sel_hi:[0,1]
	v_cvt_pk_bf16_f32 v76, v76, v77
	v_cvt_pk_bf16_f32 v77, v78, v79
	global_store_dwordx2 v[84:85], v[76:77], off
	v_pk_mul_f32 v[74:75], v[80:81], v[74:75] op_sel_hi:[0,1]
	v_cvt_pk_bf16_f32 v72, v72, v73
	v_cvt_pk_bf16_f32 v73, v74, v75
	global_store_dwordx2 v[84:85], v[72:73], off offset:32
	v_pk_mul_f32 v[70:71], v[80:81], v[70:71] op_sel_hi:[0,1]
	v_cvt_pk_bf16_f32 v68, v68, v69
	v_cvt_pk_bf16_f32 v69, v70, v71
	global_store_dwordx2 v[84:85], v[68:69], off offset:64
	v_pk_mul_f32 v[66:67], v[80:81], v[66:67] op_sel_hi:[0,1]
	v_cvt_pk_bf16_f32 v64, v64, v65
	v_cvt_pk_bf16_f32 v65, v66, v67
	global_store_dwordx2 v[84:85], v[64:65], off offset:96
	v_pk_mul_f32 v[62:63], v[80:81], v[62:63] op_sel_hi:[0,1]
	v_cvt_pk_bf16_f32 v60, v60, v61
	v_cvt_pk_bf16_f32 v61, v62, v63
	global_store_dwordx2 v[84:85], v[60:61], off offset:128
	v_pk_mul_f32 v[58:59], v[80:81], v[58:59] op_sel_hi:[0,1]
	v_cvt_pk_bf16_f32 v56, v56, v57
	v_cvt_pk_bf16_f32 v57, v58, v59
	global_store_dwordx2 v[84:85], v[56:57], off offset:160
	v_pk_mul_f32 v[54:55], v[80:81], v[54:55] op_sel_hi:[0,1]
	v_cvt_pk_bf16_f32 v52, v52, v53
	v_cvt_pk_bf16_f32 v53, v54, v55
	global_store_dwordx2 v[84:85], v[52:53], off offset:192
	v_pk_mul_f32 v[50:51], v[80:81], v[50:51] op_sel_hi:[0,1]
	v_cvt_pk_bf16_f32 v48, v48, v49
	v_cvt_pk_bf16_f32 v49, v50, v51
	global_store_dwordx2 v[84:85], v[48:49], off offset:224
	s_and_saveexec_b64 s[18:19], s[40:41]
	s_cbranch_execz .LBB0_303
	v_log_f32_e32 v50, v86
	v_readlane_b32 s20, v252, 63
	v_lshlrev_b64 v[48:49], 5, v[82:83]
	v_readlane_b32 s21, v253, 0
	s_mov_b32 s13, s53
	v_add_f32_e32 v50, v81, v50
	v_lshl_add_u64 v[48:49], s[20:21], 0, v[48:49]
	v_lshl_add_u64 v[48:49], s[12:13], 2, v[48:49]
	global_store_dword v[48:49], v50, off
	s_branch .LBB0_303
